# attention lane^16/lane^32 butterflies: ds_bpermute hops replaced by v_permlane16/32_swap (no LDS round trip)
# speedup vs baseline: 1.0039x; 1.0039x over previous
; DI float lane_get(float v, int srclane) { return __int_as_float(__builtin_amdgcn_ds_bpermute(srclane << 2, __float_as_int(v))); }
; #define LAS __attribute__((address_space(3)))
; DI float red4_sum(float v, int lane) { v += lane_get(v, lane ^ 16); v += lane_get(v, lane ^ 32); return v; }
; DI void attn_phase(const Params& p, const int layer, const int wid_s) {
;     ...
;         ps = red4_sum(ps, lane);
;         const float inv = ps > 0.f ? 1.f / ps : 0.f;
; #pragma unroll
;         for (int nt = 0; nt < 8; ++nt) s[nt] = s[nt] * inv;
;         if (cur >= 8)
; #pragma unroll
;         for (int nt = 0; nt < 8; ++nt) {
;           const float x1 = lane_get(s[nt][3], (lane - 16) & 63);
;           const float x2 = nt > 0 ? lane_get(s[nt > 0 ? nt - 1 : 0][3], (lane - 16) & 63) : 0.f;
;           const float left = fq > 0 ? x1 : x2;
;           const float im = left + 2.f * (s[nt][0] + s[nt][1] + s[nt][2]) + s[nt][3];
;           LAS float* ip = impx + (wave * 8 + nt) * 64;
;           if (hp == 0) *ip = im; else *ip += im;
.LBB0_264:
	v_mov_b32_e32 v0, v5
	s_cmp_gt_i32 s54, 7
	v_add_u32_e32 v151, s64, v177
	s_cselect_b64 s[12:13], -1, 0
	s_cmp_lt_i32 s54, 8
	s_waitcnt lgkmcnt(0)
	s_nop 1
	v_permlane16_swap_b32_e32 v0, v5
	v_add_f32_e32 v0, v5, v0
	v_mov_b32_e32 v5, v0
	v_add_u32_e32 v155, 0x80, v151
	s_waitcnt lgkmcnt(0)
	s_nop 1
	v_permlane32_swap_b32_e32 v5, v0
	v_add_f32_e32 v0, v0, v5
	v_div_scale_f32 v5, s[14:15], v0, v0, 1.0
	v_rcp_f32_e32 v114, v5
	v_div_scale_f32 v115, vcc, 1.0, v0, 1.0
	v_fma_f32 v116, -v5, v114, 1.0
	v_fmac_f32_e32 v114, v116, v114
	v_mul_f32_e32 v116, v115, v114
	v_fma_f32 v117, -v5, v116, v115
	v_fmac_f32_e32 v116, v117, v114
	v_fma_f32 v5, -v5, v116, v115
	v_div_fmas_f32 v5, v5, v114, v116
	v_div_fixup_f32 v5, v5, v0, 1.0
	v_cmp_lt_f32_e32 vcc, 0, v0
	s_nop 1
	v_cndmask_b32_e32 v0, 0, v5, vcc
	v_pk_mul_f32 v[134:135], v[124:125], v[0:1] op_sel_hi:[1,0]
	v_pk_mul_f32 v[152:153], v[6:7], v[0:1] op_sel_hi:[1,0]
	v_pk_mul_f32 v[88:89], v[88:89], v[0:1] op_sel_hi:[1,0]
	v_pk_mul_f32 v[2:3], v[2:3], v[0:1] op_sel_hi:[1,0]
	v_pk_mul_f32 v[126:127], v[94:95], v[0:1] op_sel_hi:[1,0]
	v_pk_mul_f32 v[128:129], v[92:93], v[0:1] op_sel_hi:[1,0]
	v_pk_mul_f32 v[130:131], v[96:97], v[0:1] op_sel_hi:[1,0]
	v_pk_mul_f32 v[132:133], v[90:91], v[0:1] op_sel_hi:[1,0]
	v_pk_mul_f32 v[114:115], v[102:103], v[0:1] op_sel_hi:[1,0]
	v_pk_mul_f32 v[116:117], v[100:101], v[0:1] op_sel_hi:[1,0]
	v_pk_mul_f32 v[118:119], v[104:105], v[0:1] op_sel_hi:[1,0]
	v_pk_mul_f32 v[124:125], v[98:99], v[0:1] op_sel_hi:[1,0]
	v_pk_mul_f32 v[6:7], v[110:111], v[0:1] op_sel_hi:[1,0]
	v_pk_mul_f32 v[108:109], v[108:109], v[0:1] op_sel_hi:[1,0]
	v_pk_mul_f32 v[110:111], v[112:113], v[0:1] op_sel_hi:[1,0]
	v_pk_mul_f32 v[112:113], v[106:107], v[0:1] op_sel_hi:[1,0]
	s_cbranch_scc1 .LBB0_266
	ds_bpermute_b32 v198, v181, v135
	ds_bpermute_b32 v199, v181, v89
	ds_bpermute_b32 v200, v181, v127
	ds_bpermute_b32 v201, v181, v131
	ds_bpermute_b32 v202, v181, v115
	ds_bpermute_b32 v203, v181, v119
	ds_bpermute_b32 v204, v181, v7
	ds_bpermute_b32 v205, v181, v111
	s_waitcnt lgkmcnt(0)
	v_add_f32_e32 v5, v152, v153
	v_add_f32_e32 v5, v134, v5
	v_add_f32_e32 v91, v2, v3
	v_add_f32_e32 v91, v88, v91
	v_cndmask_b32_e64 v92, v198, 0, s[62:63]
	v_fmac_f32_e32 v92, 2.0, v5
	v_add_f32_e32 v5, v135, v92
	v_cndmask_b32_e64 v0, v199, v198, s[62:63]
	v_fmac_f32_e32 v0, 2.0, v91
	v_add_f32_e32 v0, v89, v0
	ds_write2st64_b32 v155, v5, v0 offset0:88 offset1:89
	v_add_f32_e32 v5, v128, v129
	v_add_f32_e32 v5, v126, v5
	v_add_f32_e32 v91, v132, v133
	v_add_f32_e32 v91, v130, v91
	v_cndmask_b32_e64 v92, v200, v199, s[62:63]
	v_fmac_f32_e32 v92, 2.0, v5
	v_add_f32_e32 v5, v127, v92
	v_cndmask_b32_e64 v0, v201, v200, s[62:63]
	v_fmac_f32_e32 v0, 2.0, v91
	v_add_f32_e32 v0, v131, v0
	ds_write2st64_b32 v155, v5, v0 offset0:90 offset1:91
	v_add_f32_e32 v5, v116, v117
	v_add_f32_e32 v5, v114, v5
	v_add_f32_e32 v91, v124, v125
	v_add_f32_e32 v91, v118, v91
	v_cndmask_b32_e64 v92, v202, v201, s[62:63]
	v_fmac_f32_e32 v92, 2.0, v5
	v_add_f32_e32 v5, v115, v92
	v_cndmask_b32_e64 v0, v203, v202, s[62:63]
	v_fmac_f32_e32 v0, 2.0, v91
	v_add_f32_e32 v0, v119, v0
	ds_write2st64_b32 v155, v5, v0 offset0:92 offset1:93
	v_add_f32_e32 v5, v108, v109
	v_add_f32_e32 v5, v6, v5
	v_add_f32_e32 v91, v112, v113
	v_add_f32_e32 v91, v110, v91
	v_cndmask_b32_e64 v92, v204, v203, s[62:63]
	v_fmac_f32_e32 v92, 2.0, v5
	v_add_f32_e32 v5, v7, v92
	v_cndmask_b32_e64 v0, v205, v204, s[62:63]
	v_fmac_f32_e32 v0, 2.0, v91
	v_add_f32_e32 v0, v111, v0
	ds_write2st64_b32 v155, v5, v0 offset0:94 offset1:95

; DI float lane_get(float v, int srclane) { return __int_as_float(__builtin_amdgcn_ds_bpermute(srclane << 2, __float_as_int(v))); }
; #define LAS __attribute__((address_space(3)))
; DI float red4_sum(float v, int lane) { v += lane_get(v, lane ^ 16); v += lane_get(v, lane ^ 32); return v; }
; DI void attn_phase(const Params& p, const int layer, const int wid_s) {
;     ...
;         ps = red4_sum(ps, lane);
;         const float inv = ps > 0.f ? 1.f / ps : 0.f;
; #pragma unroll
;         for (int nt = 0; nt < 8; ++nt) s[nt] = s[nt] * inv;
;         if (cur >= 8)
; #pragma unroll
;         for (int nt = 0; nt < 8; ++nt) {
;           const float x1 = lane_get(s[nt][3], (lane - 16) & 63);
;           const float x2 = nt > 0 ? lane_get(s[nt > 0 ? nt - 1 : 0][3], (lane - 16) & 63) : 0.f;
;           const float left = fq > 0 ? x1 : x2;
;           const float im = left + 2.f * (s[nt][0] + s[nt][1] + s[nt][2]) + s[nt][3];
;           LAS float* ip = impx + (wave * 8 + nt) * 64;
;           if (hp == 0) *ip = im; else *ip += im;
.LBB0_324:
	v_mov_b32_e32 v0, v5
	s_waitcnt lgkmcnt(0)
	s_nop 1
	v_permlane16_swap_b32_e32 v0, v5
	v_add_f32_e32 v0, v5, v0
	v_mov_b32_e32 v5, v0
	s_waitcnt lgkmcnt(0)
	s_nop 1
	v_permlane32_swap_b32_e32 v5, v0
	v_add_f32_e32 v0, v0, v5
	v_div_scale_f32 v5, s[0:1], v0, v0, 1.0
	v_rcp_f32_e32 v24, v5
	v_div_scale_f32 v25, vcc, 1.0, v0, 1.0
	v_fma_f32 v26, -v5, v24, 1.0
	v_fmac_f32_e32 v24, v26, v24
	v_mul_f32_e32 v26, v25, v24
	v_fma_f32 v27, -v5, v26, v25
	v_fmac_f32_e32 v26, v27, v24
	v_fma_f32 v5, -v5, v26, v25
	v_div_fmas_f32 v5, v5, v24, v26
	v_div_fixup_f32 v5, v5, v0, 1.0
	v_cmp_lt_f32_e32 vcc, 0, v0
	s_nop 1
	v_cndmask_b32_e32 v0, 0, v5, vcc
	v_cndmask_b32_e64 v5, 0, 1, s[12:13]
	v_pk_mul_f32 v[2:3], v[2:3], v[0:1] op_sel_hi:[1,0]
	v_pk_mul_f32 v[24:25], v[28:29], v[0:1] op_sel_hi:[1,0]
	v_pk_mul_f32 v[26:27], v[30:31], v[0:1] op_sel_hi:[1,0]
	v_pk_mul_f32 v[28:29], v[6:7], v[0:1] op_sel_hi:[1,0]
	v_pk_mul_f32 v[54:55], v[44:45], v[0:1] op_sel_hi:[1,0]
	v_pk_mul_f32 v[56:57], v[38:39], v[0:1] op_sel_hi:[1,0]
	v_pk_mul_f32 v[58:59], v[46:47], v[0:1] op_sel_hi:[1,0]
	v_pk_mul_f32 v[60:61], v[36:37], v[0:1] op_sel_hi:[1,0]
	v_pk_mul_f32 v[46:47], v[50:51], v[0:1] op_sel_hi:[1,0]
	v_pk_mul_f32 v[48:49], v[48:49], v[0:1] op_sel_hi:[1,0]
	v_pk_mul_f32 v[50:51], v[40:41], v[0:1] op_sel_hi:[1,0]
	v_pk_mul_f32 v[52:53], v[52:53], v[0:1] op_sel_hi:[1,0]
	v_pk_mul_f32 v[6:7], v[34:35], v[0:1] op_sel_hi:[1,0]
	v_pk_mul_f32 v[40:41], v[32:33], v[0:1] op_sel_hi:[1,0]
	v_pk_mul_f32 v[42:43], v[42:43], v[0:1] op_sel_hi:[1,0]
	v_cmp_ne_u32_e64 s[0:1], 1, v5
	s_andn2_b64 vcc, exec, s[12:13]
	v_pk_mul_f32 v[44:45], v[62:63], v[0:1] op_sel_hi:[1,0]
	s_cbranch_vccnz .LBB0_326
	ds_bpermute_b32 v84, v181, v3
	ds_bpermute_b32 v85, v181, v27
	ds_bpermute_b32 v86, v181, v55
	ds_bpermute_b32 v87, v181, v59
	ds_bpermute_b32 v88, v181, v47
	ds_bpermute_b32 v89, v181, v51
	ds_bpermute_b32 v90, v181, v7
	ds_bpermute_b32 v91, v181, v43
	ds_read2st64_b32 v[92:93], v155 offset0:88 offset1:89
	ds_read2st64_b32 v[94:95], v155 offset0:90 offset1:91
	ds_read2st64_b32 v[96:97], v155 offset0:92 offset1:93
	ds_read2st64_b32 v[98:99], v155 offset0:94 offset1:95
	s_waitcnt lgkmcnt(0)
	v_add_f32_e32 v5, v24, v25
	v_add_f32_e32 v5, v2, v5
	v_add_f32_e32 v32, v28, v29
	v_add_f32_e32 v32, v26, v32
	v_cndmask_b32_e64 v30, v84, 0, s[62:63]
	v_fmac_f32_e32 v30, 2.0, v5
	v_add_f32_e32 v5, v3, v30
	v_add_f32_e32 v5, v92, v5
	v_cndmask_b32_e64 v0, v85, v84, s[62:63]
	v_fmac_f32_e32 v0, 2.0, v32
	v_add_f32_e32 v0, v27, v0
	v_add_f32_e32 v0, v93, v0
	ds_write2st64_b32 v155, v5, v0 offset0:88 offset1:89
	v_add_f32_e32 v5, v56, v57
	v_add_f32_e32 v5, v54, v5
	v_add_f32_e32 v32, v60, v61
	v_add_f32_e32 v32, v58, v32
	v_cndmask_b32_e64 v30, v86, v85, s[62:63]
	v_fmac_f32_e32 v30, 2.0, v5
	v_add_f32_e32 v5, v55, v30
	v_add_f32_e32 v5, v94, v5
	v_cndmask_b32_e64 v0, v87, v86, s[62:63]
	v_fmac_f32_e32 v0, 2.0, v32
	v_add_f32_e32 v0, v59, v0
	v_add_f32_e32 v0, v95, v0
	ds_write2st64_b32 v155, v5, v0 offset0:90 offset1:91
	v_add_f32_e32 v5, v48, v49
	v_add_f32_e32 v5, v46, v5
	v_add_f32_e32 v32, v52, v53
	v_add_f32_e32 v32, v50, v32
	v_cndmask_b32_e64 v30, v88, v87, s[62:63]
	v_fmac_f32_e32 v30, 2.0, v5
	v_add_f32_e32 v5, v47, v30
	v_add_f32_e32 v5, v96, v5
	v_cndmask_b32_e64 v0, v89, v88, s[62:63]
	v_fmac_f32_e32 v0, 2.0, v32
	v_add_f32_e32 v0, v51, v0
	v_add_f32_e32 v0, v97, v0
	ds_write2st64_b32 v155, v5, v0 offset0:92 offset1:93
	v_add_f32_e32 v5, v40, v41
	v_add_f32_e32 v5, v6, v5
	v_add_f32_e32 v32, v44, v45
	v_add_f32_e32 v32, v42, v32
	v_cndmask_b32_e64 v30, v90, v89, s[62:63]
	v_fmac_f32_e32 v30, 2.0, v5
	v_add_f32_e32 v5, v7, v30
	v_add_f32_e32 v5, v98, v5
	v_cndmask_b32_e64 v0, v91, v90, s[62:63]
	v_fmac_f32_e32 v0, 2.0, v32
	v_add_f32_e32 v0, v43, v0
	v_add_f32_e32 v0, v99, v0
	ds_write2st64_b32 v155, v5, v0 offset0:94 offset1:95

; DI void attn_phase(const Params& p, const int layer, const int wid_s) {
;     ...
;           for (int j = 0; j < 4; ++j) fin[(hp * 16 + dt * 4 + j) * 64] = o[dt][j] * gate_c;
;       }
;       unsigned mk = (2u << cur) - 1u;
;       if (cur >= 8) {
;       float impv[8];
;       __syncthreads();
; #pragma unroll
;       for (int nt = 0; nt < 8; ++nt) {
;         const float mine = impx[(wave * 8 + nt) * 64], other = impx[((wave ^ 4) * 8 + nt) * 64];
;         const float im = hpair == 0 ? mine + other : other + mine;
;         const int jb = nt * 4 + fql;
;         const bool forced = (jb == 0) || (jb == cur) || (jb == cur - 1);
;         impv[nt] = jb <= cur ? im + (forced ? 1e6f : 0.f) : NEGF;
;         impb[jb] = impv[nt];
;       }
;       __syncthreads();
.LBB0_332:
	v_cvt_f32_f16_sdwa v0, v121 dst_sel:DWORD dst_unused:UNUSED_PAD src0_sel:WORD_1
	v_mul_f32_e32 v0, 0xbfb8aa3b, v0
	v_exp_f32_e32 v0, v0
	s_nop 0
	v_add_f32_e32 v0, 1.0, v0
	v_div_scale_f32 v2, s[4:5], v0, v0, 1.0
	v_rcp_f32_e32 v3, v2
	v_div_scale_f32 v5, vcc, 1.0, v0, 1.0
	s_lshl_b32 s4, 2, s54
	v_fma_f32 v6, -v2, v3, 1.0
	v_fmac_f32_e32 v3, v6, v3
	v_mul_f32_e32 v6, v5, v3
	v_fma_f32 v7, -v2, v6, v5
	v_fmac_f32_e32 v6, v7, v3
	v_fma_f32 v2, -v2, v6, v5
	v_div_fmas_f32 v2, v2, v3, v6
	v_div_fixup_f32 v0, v2, v0, 1.0
	v_mul_f32_e32 v2, v0, v36
	v_mul_f32_e32 v3, v0, v37
	v_mul_f32_e32 v5, v0, v38
	v_mul_f32_e32 v6, v0, v39
	v_mul_f32_e32 v7, v0, v28
	ds_write2st64_b32 v188, v2, v3 offset0:168 offset1:169
	ds_write2st64_b32 v188, v5, v6 offset0:170 offset1:171
	v_mul_f32_e32 v2, v0, v29
	ds_write2st64_b32 v188, v7, v2 offset0:172 offset1:173
	v_mul_f32_e32 v2, v0, v30
	v_mul_f32_e32 v3, v0, v31
	ds_write2st64_b32 v188, v2, v3 offset0:174 offset1:175
	v_mul_f32_e32 v2, v0, v32
	v_mul_f32_e32 v3, v0, v33
	ds_write2st64_b32 v188, v2, v3 offset0:176 offset1:177
	v_mul_f32_e32 v2, v0, v34
	v_mul_f32_e32 v3, v0, v35
	ds_write2st64_b32 v188, v2, v3 offset0:178 offset1:179
	v_mul_f32_e32 v2, v0, v24
	v_mul_f32_e32 v3, v0, v25
	s_add_i32 s4, s4, -1
	ds_write2st64_b32 v188, v2, v3 offset0:180 offset1:181
	v_mul_f32_e32 v2, v0, v26
	v_mul_f32_e32 v0, v0, v27
	s_and_b64 vcc, exec, s[0:1]
	v_mov_b32_e32 v5, s4
	ds_write2st64_b32 v188, v2, v0 offset0:182 offset1:183
	s_cbranch_vccnz .LBB0_334
	s_waitcnt lgkmcnt(0)
	s_barrier
	ds_read_b32 v198, v151 offset:22656
	ds_read_b32 v199, v151 offset:22912
	ds_read_b32 v200, v151 offset:23168
	ds_read_b32 v201, v151 offset:23424
	ds_read_b32 v202, v151 offset:23680
	ds_read_b32 v203, v151 offset:23936
	ds_read_b32 v204, v151 offset:24192
	ds_read_b32 v205, v151 offset:24448
	ds_read_b32 v206, v182 offset:22656
	ds_read_b32 v207, v182 offset:22912
	ds_read_b32 v208, v182 offset:23168
	ds_read_b32 v209, v182 offset:23424
	ds_read_b32 v210, v182 offset:23680
	ds_read_b32 v211, v182 offset:23936
	ds_read_b32 v212, v182 offset:24192
	ds_read_b32 v213, v182 offset:24448
	s_add_i32 s6, s54, -1
	v_lshl_add_u32 v24, v123, 2, v147
	v_add_u32_e32 v238, 0, v123
	v_add_u32_e32 v239, 4, v123
	v_add_u32_e32 v240, 8, v123
	v_add_u32_e32 v241, 12, v123
	v_add_u32_e32 v242, 16, v123
	v_add_u32_e32 v243, 20, v123
	v_add_u32_e32 v244, 24, v123
	v_add_u32_e32 v245, 28, v123
	s_waitcnt lgkmcnt(0)
	v_cmp_eq_u32_e64 s[8:9], 0, v238
	v_cmp_eq_u32_e64 s[10:11], s54, v238
	v_cmp_eq_u32_e64 s[12:13], s6, v238
	v_add_f32_e32 v198, v198, v206
	s_or_b64 s[8:9], s[8:9], s[10:11]
	s_or_b64 s[8:9], s[8:9], s[12:13]
	v_cmp_lt_i32_e64 s[14:15], s54, v238
	s_nop 0
	v_cndmask_b32_e64 v0, 0, v159, s[8:9]
	s_nop 0
	v_add_f32_e32 v198, v0, v198
	v_cndmask_b32_e64 v39, v198, v4, s[14:15]
	ds_write_b32 v24, v39 offset:4224
	v_cmp_eq_u32_e64 s[8:9], 0, v239
	v_cmp_eq_u32_e64 s[10:11], s54, v239
	v_cmp_eq_u32_e64 s[12:13], s6, v239
	v_add_f32_e32 v199, v199, v207
	s_or_b64 s[8:9], s[8:9], s[10:11]
	s_or_b64 s[8:9], s[8:9], s[12:13]
	v_cmp_lt_i32_e64 s[14:15], s54, v239
	s_nop 0
	v_cndmask_b32_e64 v0, 0, v159, s[8:9]
	s_nop 0
	v_add_f32_e32 v199, v0, v199
	v_cndmask_b32_e64 v40, v199, v4, s[14:15]
	ds_write_b32 v24, v40 offset:4240
	v_cmp_eq_u32_e64 s[8:9], 0, v240
	v_cmp_eq_u32_e64 s[10:11], s54, v240
	v_cmp_eq_u32_e64 s[12:13], s6, v240
	v_add_f32_e32 v200, v200, v208
	s_or_b64 s[8:9], s[8:9], s[10:11]
	s_or_b64 s[8:9], s[8:9], s[12:13]
	v_cmp_lt_i32_e64 s[14:15], s54, v240
	s_nop 0
	v_cndmask_b32_e64 v0, 0, v159, s[8:9]
	s_nop 0
	v_add_f32_e32 v200, v0, v200
	v_cndmask_b32_e64 v38, v200, v4, s[14:15]
	ds_write_b32 v24, v38 offset:4256
	v_cmp_eq_u32_e64 s[8:9], 0, v241
	v_cmp_eq_u32_e64 s[10:11], s54, v241
	v_cmp_eq_u32_e64 s[12:13], s6, v241
	v_add_f32_e32 v201, v201, v209
	s_or_b64 s[8:9], s[8:9], s[10:11]
	s_or_b64 s[8:9], s[8:9], s[12:13]
	v_cmp_lt_i32_e64 s[14:15], s54, v241
	s_nop 0
	v_cndmask_b32_e64 v0, 0, v159, s[8:9]
	s_nop 0
	v_add_f32_e32 v201, v0, v201
	v_cndmask_b32_e64 v37, v201, v4, s[14:15]
	ds_write_b32 v24, v37 offset:4272
	v_cmp_eq_u32_e64 s[8:9], 0, v242
	v_cmp_eq_u32_e64 s[10:11], s54, v242
	v_cmp_eq_u32_e64 s[12:13], s6, v242
	v_add_f32_e32 v202, v202, v210
	s_or_b64 s[8:9], s[8:9], s[10:11]
	s_or_b64 s[8:9], s[8:9], s[12:13]
	v_cmp_lt_i32_e64 s[14:15], s54, v242
	s_nop 0
	v_cndmask_b32_e64 v0, 0, v159, s[8:9]
	s_nop 0
	v_add_f32_e32 v202, v0, v202
	v_cndmask_b32_e64 v36, v202, v4, s[14:15]
	ds_write_b32 v24, v36 offset:4288
	v_cmp_eq_u32_e64 s[8:9], 0, v243
	v_cmp_eq_u32_e64 s[10:11], s54, v243
	v_cmp_eq_u32_e64 s[12:13], s6, v243
	v_add_f32_e32 v203, v203, v211
	s_or_b64 s[8:9], s[8:9], s[10:11]
	s_or_b64 s[8:9], s[8:9], s[12:13]
	v_cmp_lt_i32_e64 s[14:15], s54, v243
	s_nop 0
	v_cndmask_b32_e64 v0, 0, v159, s[8:9]
	s_nop 0
	v_add_f32_e32 v203, v0, v203
	v_cndmask_b32_e64 v35, v203, v4, s[14:15]
	ds_write_b32 v24, v35 offset:4304
	v_cmp_eq_u32_e64 s[8:9], 0, v244
	v_cmp_eq_u32_e64 s[10:11], s54, v244
	v_cmp_eq_u32_e64 s[12:13], s6, v244
	v_add_f32_e32 v204, v204, v212
	s_or_b64 s[8:9], s[8:9], s[10:11]
	s_or_b64 s[8:9], s[8:9], s[12:13]
	v_cmp_lt_i32_e64 s[14:15], s54, v244
	s_nop 0
	v_cndmask_b32_e64 v0, 0, v159, s[8:9]
	s_nop 0
	v_add_f32_e32 v204, v0, v204
	v_cndmask_b32_e64 v34, v204, v4, s[14:15]
	ds_write_b32 v24, v34 offset:4320
	v_cmp_eq_u32_e64 s[8:9], 0, v245
	v_cmp_eq_u32_e64 s[10:11], s54, v245
	v_cmp_eq_u32_e64 s[12:13], s6, v245
	v_add_f32_e32 v205, v205, v213
	s_or_b64 s[8:9], s[8:9], s[10:11]
	s_or_b64 s[8:9], s[8:9], s[12:13]
	v_cmp_lt_i32_e64 s[14:15], s54, v245
	s_nop 0
	v_cndmask_b32_e64 v0, 0, v159, s[8:9]
	s_nop 0
	v_add_f32_e32 v205, v0, v205
	v_cndmask_b32_e64 v33, v205, v4, s[14:15]
	ds_write_b32 v24, v33 offset:4336
	s_waitcnt lgkmcnt(0)
	s_barrier
; #define LAS __attribute__((address_space(3)))
; DI void attn_phase(const Params& p, const int layer, const int wid_s) {
;     ...
;       int cnt[8];
; #pragma unroll
;       for (int nt = 0; nt < 8; ++nt) cnt[nt] = 0;
; #pragma unroll
;       for (int i = 0; i < 8; ++i) {
;         const f32x4 r4 = *(const LAS f32x4*)(impb + 4 * i);
;         const float rv[4] = {r4[0], r4[1], r4[2], r4[3]};
; #pragma unroll
;         for (int nt = 0; nt < 8; ++nt) {
;           const float a = impv[nt]; const int ja = nt * 4 + fql;
; #pragma unroll
;           for (int c = 0; c < 4; ++c) cnt[nt] += (int)(rv[c] > a) | ((int)(rv[c] == a) & (int)((4 * i + c) < ja));
;         }
;       }
	ds_read_b128 v[198:201], v147 offset:4224
	ds_read_b128 v[202:205], v147 offset:4240
	ds_read_b128 v[206:209], v147 offset:4256
	ds_read_b128 v[210:213], v147 offset:4272
	ds_read_b128 v[214:217], v147 offset:4288
	ds_read_b128 v[218:221], v147 offset:4304
	ds_read_b128 v[222:225], v147 offset:4320
	ds_read_b128 v[226:229], v147 offset:4336
	v_cmp_lt_i32_e64 s[6:7], 0, v123
	v_cmp_lt_i32_e64 s[8:9], 1, v123
	v_cmp_lt_i32_e64 s[10:11], 2, v123
	v_mov_b32_e32 v230, 0
	v_mov_b32_e32 v231, 0
	v_mov_b32_e32 v232, 0
	v_mov_b32_e32 v233, 0
	v_mov_b32_e32 v234, 0
	v_mov_b32_e32 v235, 0
	v_mov_b32_e32 v236, 0
	v_mov_b32_e32 v237, 0
	s_waitcnt lgkmcnt(0)
	v_cmp_gt_f32_e64 s[12:13], v198, v39
	v_cmp_ge_f32_e64 s[20:21], v198, v39
	s_and_b64 s[20:21], s[20:21], s[6:7]
	s_or_b64 s[12:13], s[12:13], s[20:21]
	v_cmp_gt_f32_e64 s[14:15], v199, v39
	v_cmp_ge_f32_e64 s[20:21], v199, v39
	s_and_b64 s[20:21], s[20:21], s[8:9]
	s_or_b64 s[14:15], s[14:15], s[20:21]
	v_cmp_gt_f32_e64 s[16:17], v200, v39
	v_cmp_ge_f32_e64 s[20:21], v200, v39
	s_and_b64 s[20:21], s[20:21], s[10:11]
	s_or_b64 s[16:17], s[16:17], s[20:21]
	v_addc_co_u32_e64 v230, s[18:19], 0, v230, s[12:13]
	v_cmp_gt_f32_e64 s[12:13], v201, v39
	v_addc_co_u32_e64 v230, s[18:19], 0, v230, s[14:15]
	v_cmp_gt_f32_e64 s[14:15], v202, v39
	v_addc_co_u32_e64 v230, s[18:19], 0, v230, s[16:17]
	v_cmp_gt_f32_e64 s[16:17], v203, v39
	v_addc_co_u32_e64 v230, s[18:19], 0, v230, s[12:13]
	v_cmp_gt_f32_e64 s[12:13], v204, v39
	v_addc_co_u32_e64 v230, s[18:19], 0, v230, s[14:15]
	v_cmp_gt_f32_e64 s[14:15], v205, v39
	v_addc_co_u32_e64 v230, s[18:19], 0, v230, s[16:17]
	v_cmp_gt_f32_e64 s[16:17], v206, v39
	v_addc_co_u32_e64 v230, s[18:19], 0, v230, s[12:13]
	v_cmp_gt_f32_e64 s[12:13], v207, v39
	v_addc_co_u32_e64 v230, s[18:19], 0, v230, s[14:15]
	v_cmp_gt_f32_e64 s[14:15], v208, v39
	v_addc_co_u32_e64 v230, s[18:19], 0, v230, s[16:17]
	v_cmp_gt_f32_e64 s[16:17], v209, v39
	v_addc_co_u32_e64 v230, s[18:19], 0, v230, s[12:13]
	v_cmp_gt_f32_e64 s[12:13], v210, v39
	v_addc_co_u32_e64 v230, s[18:19], 0, v230, s[14:15]
	v_cmp_gt_f32_e64 s[14:15], v211, v39
	v_addc_co_u32_e64 v230, s[18:19], 0, v230, s[16:17]
	v_cmp_gt_f32_e64 s[16:17], v212, v39
	v_addc_co_u32_e64 v230, s[18:19], 0, v230, s[12:13]
	v_cmp_gt_f32_e64 s[12:13], v213, v39
	v_addc_co_u32_e64 v230, s[18:19], 0, v230, s[14:15]
	v_cmp_gt_f32_e64 s[14:15], v214, v39
	v_addc_co_u32_e64 v230, s[18:19], 0, v230, s[16:17]
	v_cmp_gt_f32_e64 s[16:17], v215, v39
	v_addc_co_u32_e64 v230, s[18:19], 0, v230, s[12:13]
	v_cmp_gt_f32_e64 s[12:13], v216, v39
	v_addc_co_u32_e64 v230, s[18:19], 0, v230, s[14:15]
	v_cmp_gt_f32_e64 s[14:15], v217, v39
	v_addc_co_u32_e64 v230, s[18:19], 0, v230, s[16:17]
	v_cmp_gt_f32_e64 s[16:17], v218, v39
	v_addc_co_u32_e64 v230, s[18:19], 0, v230, s[12:13]
	v_cmp_gt_f32_e64 s[12:13], v219, v39
	v_addc_co_u32_e64 v230, s[18:19], 0, v230, s[14:15]
	v_cmp_gt_f32_e64 s[14:15], v220, v39
	v_addc_co_u32_e64 v230, s[18:19], 0, v230, s[16:17]
	v_cmp_gt_f32_e64 s[16:17], v221, v39
	v_addc_co_u32_e64 v230, s[18:19], 0, v230, s[12:13]
	v_cmp_gt_f32_e64 s[12:13], v222, v39
	v_addc_co_u32_e64 v230, s[18:19], 0, v230, s[14:15]
	v_cmp_gt_f32_e64 s[14:15], v223, v39
	v_addc_co_u32_e64 v230, s[18:19], 0, v230, s[16:17]
	v_cmp_gt_f32_e64 s[16:17], v224, v39
	v_addc_co_u32_e64 v230, s[18:19], 0, v230, s[12:13]
	v_cmp_gt_f32_e64 s[12:13], v225, v39
	v_addc_co_u32_e64 v230, s[18:19], 0, v230, s[14:15]
	v_cmp_gt_f32_e64 s[14:15], v226, v39
	v_addc_co_u32_e64 v230, s[18:19], 0, v230, s[16:17]
	v_cmp_gt_f32_e64 s[16:17], v227, v39
	v_addc_co_u32_e64 v230, s[18:19], 0, v230, s[12:13]
	v_cmp_gt_f32_e64 s[12:13], v228, v39
	v_addc_co_u32_e64 v230, s[18:19], 0, v230, s[14:15]
	v_cmp_gt_f32_e64 s[14:15], v229, v39
	v_addc_co_u32_e64 v230, s[18:19], 0, v230, s[16:17]
	v_cmp_ge_f32_e64 s[16:17], v198, v40
	v_addc_co_u32_e64 v230, s[18:19], 0, v230, s[12:13]
	v_cmp_ge_f32_e64 s[12:13], v199, v40
	v_addc_co_u32_e64 v230, s[18:19], 0, v230, s[14:15]
	v_cmp_ge_f32_e64 s[14:15], v200, v40
	v_addc_co_u32_e64 v231, s[18:19], 0, v231, s[16:17]
	v_cmp_ge_f32_e64 s[16:17], v201, v40
	v_addc_co_u32_e64 v231, s[18:19], 0, v231, s[12:13]
	v_cmp_gt_f32_e64 s[12:13], v202, v40
	v_cmp_ge_f32_e64 s[20:21], v202, v40
	s_and_b64 s[20:21], s[20:21], s[6:7]
	s_or_b64 s[12:13], s[12:13], s[20:21]
	v_addc_co_u32_e64 v231, s[18:19], 0, v231, s[14:15]
	v_cmp_gt_f32_e64 s[14:15], v203, v40
	v_cmp_ge_f32_e64 s[20:21], v203, v40
	s_and_b64 s[20:21], s[20:21], s[8:9]
	s_or_b64 s[14:15], s[14:15], s[20:21]
	v_addc_co_u32_e64 v231, s[18:19], 0, v231, s[16:17]
	v_cmp_gt_f32_e64 s[16:17], v204, v40
	v_cmp_ge_f32_e64 s[20:21], v204, v40
	s_and_b64 s[20:21], s[20:21], s[10:11]
	s_or_b64 s[16:17], s[16:17], s[20:21]
	v_addc_co_u32_e64 v231, s[18:19], 0, v231, s[12:13]
	v_cmp_gt_f32_e64 s[12:13], v205, v40
	v_addc_co_u32_e64 v231, s[18:19], 0, v231, s[14:15]
	v_cmp_gt_f32_e64 s[14:15], v206, v40
	v_addc_co_u32_e64 v231, s[18:19], 0, v231, s[16:17]
	v_cmp_gt_f32_e64 s[16:17], v207, v40
	v_addc_co_u32_e64 v231, s[18:19], 0, v231, s[12:13]
	v_cmp_gt_f32_e64 s[12:13], v208, v40
	v_addc_co_u32_e64 v231, s[18:19], 0, v231, s[14:15]
	v_cmp_gt_f32_e64 s[14:15], v209, v40
	v_addc_co_u32_e64 v231, s[18:19], 0, v231, s[16:17]
	v_cmp_gt_f32_e64 s[16:17], v210, v40
	v_addc_co_u32_e64 v231, s[18:19], 0, v231, s[12:13]
	v_cmp_gt_f32_e64 s[12:13], v211, v40
	v_addc_co_u32_e64 v231, s[18:19], 0, v231, s[14:15]
	v_cmp_gt_f32_e64 s[14:15], v212, v40
	v_addc_co_u32_e64 v231, s[18:19], 0, v231, s[16:17]
	v_cmp_gt_f32_e64 s[16:17], v213, v40
	v_addc_co_u32_e64 v231, s[18:19], 0, v231, s[12:13]
	v_cmp_gt_f32_e64 s[12:13], v214, v40
; #define LAS __attribute__((address_space(3)))
; DI void attn_phase(const Params& p, const int layer, const int wid_s) {
;     ...
;       for (int i = 0; i < 8; ++i) {
;         const f32x4 r4 = *(const LAS f32x4*)(impb + 4 * i);
;         const float rv[4] = {r4[0], r4[1], r4[2], r4[3]};
; #pragma unroll
;         for (int nt = 0; nt < 8; ++nt) {
;           const float a = impv[nt]; const int ja = nt * 4 + fql;
; #pragma unroll
;           for (int c = 0; c < 4; ++c) cnt[nt] += (int)(rv[c] > a) | ((int)(rv[c] == a) & (int)((4 * i + c) < ja));
;         }
;       }
	v_addc_co_u32_e64 v231, s[18:19], 0, v231, s[14:15]
	v_cmp_gt_f32_e64 s[14:15], v215, v40
	v_addc_co_u32_e64 v231, s[18:19], 0, v231, s[16:17]
	v_cmp_gt_f32_e64 s[16:17], v216, v40
	v_addc_co_u32_e64 v231, s[18:19], 0, v231, s[12:13]
	v_cmp_gt_f32_e64 s[12:13], v217, v40
	v_addc_co_u32_e64 v231, s[18:19], 0, v231, s[14:15]
	v_cmp_gt_f32_e64 s[14:15], v218, v40
	v_addc_co_u32_e64 v231, s[18:19], 0, v231, s[16:17]
	v_cmp_gt_f32_e64 s[16:17], v219, v40
	v_addc_co_u32_e64 v231, s[18:19], 0, v231, s[12:13]
	v_cmp_gt_f32_e64 s[12:13], v220, v40
	v_addc_co_u32_e64 v231, s[18:19], 0, v231, s[14:15]
	v_cmp_gt_f32_e64 s[14:15], v221, v40
	v_addc_co_u32_e64 v231, s[18:19], 0, v231, s[16:17]
	v_cmp_gt_f32_e64 s[16:17], v222, v40
	v_addc_co_u32_e64 v231, s[18:19], 0, v231, s[12:13]
	v_cmp_gt_f32_e64 s[12:13], v223, v40
	v_addc_co_u32_e64 v231, s[18:19], 0, v231, s[14:15]
	v_cmp_gt_f32_e64 s[14:15], v224, v40
	v_addc_co_u32_e64 v231, s[18:19], 0, v231, s[16:17]
	v_cmp_gt_f32_e64 s[16:17], v225, v40
	v_addc_co_u32_e64 v231, s[18:19], 0, v231, s[12:13]
	v_cmp_gt_f32_e64 s[12:13], v226, v40
	v_addc_co_u32_e64 v231, s[18:19], 0, v231, s[14:15]
	v_cmp_gt_f32_e64 s[14:15], v227, v40
	v_addc_co_u32_e64 v231, s[18:19], 0, v231, s[16:17]
	v_cmp_gt_f32_e64 s[16:17], v228, v40
	v_addc_co_u32_e64 v231, s[18:19], 0, v231, s[12:13]
	v_cmp_gt_f32_e64 s[12:13], v229, v40
	v_addc_co_u32_e64 v231, s[18:19], 0, v231, s[14:15]
	v_cmp_ge_f32_e64 s[14:15], v198, v38
	v_addc_co_u32_e64 v231, s[18:19], 0, v231, s[16:17]
	v_cmp_ge_f32_e64 s[16:17], v199, v38
	v_addc_co_u32_e64 v231, s[18:19], 0, v231, s[12:13]
	v_cmp_ge_f32_e64 s[12:13], v200, v38
	v_addc_co_u32_e64 v232, s[18:19], 0, v232, s[14:15]
	v_cmp_ge_f32_e64 s[14:15], v201, v38
	v_addc_co_u32_e64 v232, s[18:19], 0, v232, s[16:17]
	v_cmp_ge_f32_e64 s[16:17], v202, v38
	v_addc_co_u32_e64 v232, s[18:19], 0, v232, s[12:13]
	v_cmp_ge_f32_e64 s[12:13], v203, v38
	v_addc_co_u32_e64 v232, s[18:19], 0, v232, s[14:15]
	v_cmp_ge_f32_e64 s[14:15], v204, v38
	v_addc_co_u32_e64 v232, s[18:19], 0, v232, s[16:17]
	v_cmp_ge_f32_e64 s[16:17], v205, v38
	v_addc_co_u32_e64 v232, s[18:19], 0, v232, s[12:13]
	v_cmp_gt_f32_e64 s[12:13], v206, v38
	v_cmp_ge_f32_e64 s[20:21], v206, v38
	s_and_b64 s[20:21], s[20:21], s[6:7]
	s_or_b64 s[12:13], s[12:13], s[20:21]
	v_addc_co_u32_e64 v232, s[18:19], 0, v232, s[14:15]
	v_cmp_gt_f32_e64 s[14:15], v207, v38
	v_cmp_ge_f32_e64 s[20:21], v207, v38
	s_and_b64 s[20:21], s[20:21], s[8:9]
	s_or_b64 s[14:15], s[14:15], s[20:21]
	v_addc_co_u32_e64 v232, s[18:19], 0, v232, s[16:17]
	v_cmp_gt_f32_e64 s[16:17], v208, v38
	v_cmp_ge_f32_e64 s[20:21], v208, v38
	s_and_b64 s[20:21], s[20:21], s[10:11]
	s_or_b64 s[16:17], s[16:17], s[20:21]
	v_addc_co_u32_e64 v232, s[18:19], 0, v232, s[12:13]
	v_cmp_gt_f32_e64 s[12:13], v209, v38
	v_addc_co_u32_e64 v232, s[18:19], 0, v232, s[14:15]
	v_cmp_gt_f32_e64 s[14:15], v210, v38
	v_addc_co_u32_e64 v232, s[18:19], 0, v232, s[16:17]
	v_cmp_gt_f32_e64 s[16:17], v211, v38
	v_addc_co_u32_e64 v232, s[18:19], 0, v232, s[12:13]
	v_cmp_gt_f32_e64 s[12:13], v212, v38
	v_addc_co_u32_e64 v232, s[18:19], 0, v232, s[14:15]
	v_cmp_gt_f32_e64 s[14:15], v213, v38
	v_addc_co_u32_e64 v232, s[18:19], 0, v232, s[16:17]
	v_cmp_gt_f32_e64 s[16:17], v214, v38
	v_addc_co_u32_e64 v232, s[18:19], 0, v232, s[12:13]
	v_cmp_gt_f32_e64 s[12:13], v215, v38
	v_addc_co_u32_e64 v232, s[18:19], 0, v232, s[14:15]
	v_cmp_gt_f32_e64 s[14:15], v216, v38
	v_addc_co_u32_e64 v232, s[18:19], 0, v232, s[16:17]
	v_cmp_gt_f32_e64 s[16:17], v217, v38
	v_addc_co_u32_e64 v232, s[18:19], 0, v232, s[12:13]
	v_cmp_gt_f32_e64 s[12:13], v218, v38
	v_addc_co_u32_e64 v232, s[18:19], 0, v232, s[14:15]
	v_cmp_gt_f32_e64 s[14:15], v219, v38
	v_addc_co_u32_e64 v232, s[18:19], 0, v232, s[16:17]
	v_cmp_gt_f32_e64 s[16:17], v220, v38
	v_addc_co_u32_e64 v232, s[18:19], 0, v232, s[12:13]
	v_cmp_gt_f32_e64 s[12:13], v221, v38
	v_addc_co_u32_e64 v232, s[18:19], 0, v232, s[14:15]
	v_cmp_gt_f32_e64 s[14:15], v222, v38
	v_addc_co_u32_e64 v232, s[18:19], 0, v232, s[16:17]
	v_cmp_gt_f32_e64 s[16:17], v223, v38
	v_addc_co_u32_e64 v232, s[18:19], 0, v232, s[12:13]
	v_cmp_gt_f32_e64 s[12:13], v224, v38
	v_addc_co_u32_e64 v232, s[18:19], 0, v232, s[14:15]
	v_cmp_gt_f32_e64 s[14:15], v225, v38
	v_addc_co_u32_e64 v232, s[18:19], 0, v232, s[16:17]
	v_cmp_gt_f32_e64 s[16:17], v226, v38
	v_addc_co_u32_e64 v232, s[18:19], 0, v232, s[12:13]
	v_cmp_gt_f32_e64 s[12:13], v227, v38
	v_addc_co_u32_e64 v232, s[18:19], 0, v232, s[14:15]
	v_cmp_gt_f32_e64 s[14:15], v228, v38
	v_addc_co_u32_e64 v232, s[18:19], 0, v232, s[16:17]
	v_cmp_gt_f32_e64 s[16:17], v229, v38
	v_addc_co_u32_e64 v232, s[18:19], 0, v232, s[12:13]
	v_cmp_ge_f32_e64 s[12:13], v198, v37
	v_addc_co_u32_e64 v232, s[18:19], 0, v232, s[14:15]
	v_cmp_ge_f32_e64 s[14:15], v199, v37
	v_addc_co_u32_e64 v232, s[18:19], 0, v232, s[16:17]
	v_cmp_ge_f32_e64 s[16:17], v200, v37
	v_addc_co_u32_e64 v233, s[18:19], 0, v233, s[12:13]
	v_cmp_ge_f32_e64 s[12:13], v201, v37
	v_addc_co_u32_e64 v233, s[18:19], 0, v233, s[14:15]
	v_cmp_ge_f32_e64 s[14:15], v202, v37
	v_addc_co_u32_e64 v233, s[18:19], 0, v233, s[16:17]
	v_cmp_ge_f32_e64 s[16:17], v203, v37
	v_addc_co_u32_e64 v233, s[18:19], 0, v233, s[12:13]
	v_cmp_ge_f32_e64 s[12:13], v204, v37
	v_addc_co_u32_e64 v233, s[18:19], 0, v233, s[14:15]
	v_cmp_ge_f32_e64 s[14:15], v205, v37
	v_addc_co_u32_e64 v233, s[18:19], 0, v233, s[16:17]
	v_cmp_ge_f32_e64 s[16:17], v206, v37
	v_addc_co_u32_e64 v233, s[18:19], 0, v233, s[12:13]
	v_cmp_ge_f32_e64 s[12:13], v207, v37
	v_addc_co_u32_e64 v233, s[18:19], 0, v233, s[14:15]
	v_cmp_ge_f32_e64 s[14:15], v208, v37
; #define LAS __attribute__((address_space(3)))
; DI void attn_phase(const Params& p, const int layer, const int wid_s) {
;     ...
;       for (int i = 0; i < 8; ++i) {
;         const f32x4 r4 = *(const LAS f32x4*)(impb + 4 * i);
;         const float rv[4] = {r4[0], r4[1], r4[2], r4[3]};
; #pragma unroll
;         for (int nt = 0; nt < 8; ++nt) {
;           const float a = impv[nt]; const int ja = nt * 4 + fql;
; #pragma unroll
;           for (int c = 0; c < 4; ++c) cnt[nt] += (int)(rv[c] > a) | ((int)(rv[c] == a) & (int)((4 * i + c) < ja));
;         }
;       }
	v_addc_co_u32_e64 v233, s[18:19], 0, v233, s[16:17]
	v_cmp_ge_f32_e64 s[16:17], v209, v37
	v_addc_co_u32_e64 v233, s[18:19], 0, v233, s[12:13]
	v_cmp_gt_f32_e64 s[12:13], v210, v37
	v_cmp_ge_f32_e64 s[20:21], v210, v37
	s_and_b64 s[20:21], s[20:21], s[6:7]
	s_or_b64 s[12:13], s[12:13], s[20:21]
	v_addc_co_u32_e64 v233, s[18:19], 0, v233, s[14:15]
	v_cmp_gt_f32_e64 s[14:15], v211, v37
	v_cmp_ge_f32_e64 s[20:21], v211, v37
	s_and_b64 s[20:21], s[20:21], s[8:9]
	s_or_b64 s[14:15], s[14:15], s[20:21]
	v_addc_co_u32_e64 v233, s[18:19], 0, v233, s[16:17]
	v_cmp_gt_f32_e64 s[16:17], v212, v37
	v_cmp_ge_f32_e64 s[20:21], v212, v37
	s_and_b64 s[20:21], s[20:21], s[10:11]
	s_or_b64 s[16:17], s[16:17], s[20:21]
	v_addc_co_u32_e64 v233, s[18:19], 0, v233, s[12:13]
	v_cmp_gt_f32_e64 s[12:13], v213, v37
	v_addc_co_u32_e64 v233, s[18:19], 0, v233, s[14:15]
	v_cmp_gt_f32_e64 s[14:15], v214, v37
	v_addc_co_u32_e64 v233, s[18:19], 0, v233, s[16:17]
	v_cmp_gt_f32_e64 s[16:17], v215, v37
	v_addc_co_u32_e64 v233, s[18:19], 0, v233, s[12:13]
	v_cmp_gt_f32_e64 s[12:13], v216, v37
	v_addc_co_u32_e64 v233, s[18:19], 0, v233, s[14:15]
	v_cmp_gt_f32_e64 s[14:15], v217, v37
	v_addc_co_u32_e64 v233, s[18:19], 0, v233, s[16:17]
	v_cmp_gt_f32_e64 s[16:17], v218, v37
	v_addc_co_u32_e64 v233, s[18:19], 0, v233, s[12:13]
	v_cmp_gt_f32_e64 s[12:13], v219, v37
	v_addc_co_u32_e64 v233, s[18:19], 0, v233, s[14:15]
	v_cmp_gt_f32_e64 s[14:15], v220, v37
	v_addc_co_u32_e64 v233, s[18:19], 0, v233, s[16:17]
	v_cmp_gt_f32_e64 s[16:17], v221, v37
	v_addc_co_u32_e64 v233, s[18:19], 0, v233, s[12:13]
	v_cmp_gt_f32_e64 s[12:13], v222, v37
	v_addc_co_u32_e64 v233, s[18:19], 0, v233, s[14:15]
	v_cmp_gt_f32_e64 s[14:15], v223, v37
	v_addc_co_u32_e64 v233, s[18:19], 0, v233, s[16:17]
	v_cmp_gt_f32_e64 s[16:17], v224, v37
	v_addc_co_u32_e64 v233, s[18:19], 0, v233, s[12:13]
	v_cmp_gt_f32_e64 s[12:13], v225, v37
	v_addc_co_u32_e64 v233, s[18:19], 0, v233, s[14:15]
	v_cmp_gt_f32_e64 s[14:15], v226, v37
	v_addc_co_u32_e64 v233, s[18:19], 0, v233, s[16:17]
	v_cmp_gt_f32_e64 s[16:17], v227, v37
	v_addc_co_u32_e64 v233, s[18:19], 0, v233, s[12:13]
	v_cmp_gt_f32_e64 s[12:13], v228, v37
	v_addc_co_u32_e64 v233, s[18:19], 0, v233, s[14:15]
	v_cmp_gt_f32_e64 s[14:15], v229, v37
	v_addc_co_u32_e64 v233, s[18:19], 0, v233, s[16:17]
	v_cmp_ge_f32_e64 s[16:17], v198, v36
	v_addc_co_u32_e64 v233, s[18:19], 0, v233, s[12:13]
	v_cmp_ge_f32_e64 s[12:13], v199, v36
	v_addc_co_u32_e64 v233, s[18:19], 0, v233, s[14:15]
	v_cmp_ge_f32_e64 s[14:15], v200, v36
	v_addc_co_u32_e64 v234, s[18:19], 0, v234, s[16:17]
	v_cmp_ge_f32_e64 s[16:17], v201, v36
	v_addc_co_u32_e64 v234, s[18:19], 0, v234, s[12:13]
	v_cmp_ge_f32_e64 s[12:13], v202, v36
	v_addc_co_u32_e64 v234, s[18:19], 0, v234, s[14:15]
	v_cmp_ge_f32_e64 s[14:15], v203, v36
	v_addc_co_u32_e64 v234, s[18:19], 0, v234, s[16:17]
	v_cmp_ge_f32_e64 s[16:17], v204, v36
	v_addc_co_u32_e64 v234, s[18:19], 0, v234, s[12:13]
	v_cmp_ge_f32_e64 s[12:13], v205, v36
	v_addc_co_u32_e64 v234, s[18:19], 0, v234, s[14:15]
	v_cmp_ge_f32_e64 s[14:15], v206, v36
	v_addc_co_u32_e64 v234, s[18:19], 0, v234, s[16:17]
	v_cmp_ge_f32_e64 s[16:17], v207, v36
	v_addc_co_u32_e64 v234, s[18:19], 0, v234, s[12:13]
	v_cmp_ge_f32_e64 s[12:13], v208, v36
	v_addc_co_u32_e64 v234, s[18:19], 0, v234, s[14:15]
	v_cmp_ge_f32_e64 s[14:15], v209, v36
	v_addc_co_u32_e64 v234, s[18:19], 0, v234, s[16:17]
	v_cmp_ge_f32_e64 s[16:17], v210, v36
	v_addc_co_u32_e64 v234, s[18:19], 0, v234, s[12:13]
	v_cmp_ge_f32_e64 s[12:13], v211, v36
	v_addc_co_u32_e64 v234, s[18:19], 0, v234, s[14:15]
	v_cmp_ge_f32_e64 s[14:15], v212, v36
	v_addc_co_u32_e64 v234, s[18:19], 0, v234, s[16:17]
	v_cmp_ge_f32_e64 s[16:17], v213, v36
	v_addc_co_u32_e64 v234, s[18:19], 0, v234, s[12:13]
	v_cmp_gt_f32_e64 s[12:13], v214, v36
	v_cmp_ge_f32_e64 s[20:21], v214, v36
	s_and_b64 s[20:21], s[20:21], s[6:7]
	s_or_b64 s[12:13], s[12:13], s[20:21]
	v_addc_co_u32_e64 v234, s[18:19], 0, v234, s[14:15]
	v_cmp_gt_f32_e64 s[14:15], v215, v36
	v_cmp_ge_f32_e64 s[20:21], v215, v36
	s_and_b64 s[20:21], s[20:21], s[8:9]
	s_or_b64 s[14:15], s[14:15], s[20:21]
	v_addc_co_u32_e64 v234, s[18:19], 0, v234, s[16:17]
	v_cmp_gt_f32_e64 s[16:17], v216, v36
	v_cmp_ge_f32_e64 s[20:21], v216, v36
	s_and_b64 s[20:21], s[20:21], s[10:11]
	s_or_b64 s[16:17], s[16:17], s[20:21]
	v_addc_co_u32_e64 v234, s[18:19], 0, v234, s[12:13]
	v_cmp_gt_f32_e64 s[12:13], v217, v36
	v_addc_co_u32_e64 v234, s[18:19], 0, v234, s[14:15]
	v_cmp_gt_f32_e64 s[14:15], v218, v36
	v_addc_co_u32_e64 v234, s[18:19], 0, v234, s[16:17]
	v_cmp_gt_f32_e64 s[16:17], v219, v36
	v_addc_co_u32_e64 v234, s[18:19], 0, v234, s[12:13]
	v_cmp_gt_f32_e64 s[12:13], v220, v36
	v_addc_co_u32_e64 v234, s[18:19], 0, v234, s[14:15]
	v_cmp_gt_f32_e64 s[14:15], v221, v36
	v_addc_co_u32_e64 v234, s[18:19], 0, v234, s[16:17]
	v_cmp_gt_f32_e64 s[16:17], v222, v36
	v_addc_co_u32_e64 v234, s[18:19], 0, v234, s[12:13]
	v_cmp_gt_f32_e64 s[12:13], v223, v36
	v_addc_co_u32_e64 v234, s[18:19], 0, v234, s[14:15]
	v_cmp_gt_f32_e64 s[14:15], v224, v36
	v_addc_co_u32_e64 v234, s[18:19], 0, v234, s[16:17]
	v_cmp_gt_f32_e64 s[16:17], v225, v36
	v_addc_co_u32_e64 v234, s[18:19], 0, v234, s[12:13]
	v_cmp_gt_f32_e64 s[12:13], v226, v36
	v_addc_co_u32_e64 v234, s[18:19], 0, v234, s[14:15]
	v_cmp_gt_f32_e64 s[14:15], v227, v36
	v_addc_co_u32_e64 v234, s[18:19], 0, v234, s[16:17]
	v_cmp_gt_f32_e64 s[16:17], v228, v36
	v_addc_co_u32_e64 v234, s[18:19], 0, v234, s[12:13]
	v_cmp_gt_f32_e64 s[12:13], v229, v36
	v_addc_co_u32_e64 v234, s[18:19], 0, v234, s[14:15]
	v_cmp_ge_f32_e64 s[14:15], v198, v35
	v_addc_co_u32_e64 v234, s[18:19], 0, v234, s[16:17]
; #define LAS __attribute__((address_space(3)))
; DI void attn_phase(const Params& p, const int layer, const int wid_s) {
;     ...
;       for (int i = 0; i < 8; ++i) {
;         const f32x4 r4 = *(const LAS f32x4*)(impb + 4 * i);
;         const float rv[4] = {r4[0], r4[1], r4[2], r4[3]};
; #pragma unroll
;         for (int nt = 0; nt < 8; ++nt) {
;           const float a = impv[nt]; const int ja = nt * 4 + fql;
; #pragma unroll
;           for (int c = 0; c < 4; ++c) cnt[nt] += (int)(rv[c] > a) | ((int)(rv[c] == a) & (int)((4 * i + c) < ja));
;         }
;       }
	v_cmp_ge_f32_e64 s[16:17], v199, v35
	v_addc_co_u32_e64 v234, s[18:19], 0, v234, s[12:13]
	v_cmp_ge_f32_e64 s[12:13], v200, v35
	v_addc_co_u32_e64 v235, s[18:19], 0, v235, s[14:15]
	v_cmp_ge_f32_e64 s[14:15], v201, v35
	v_addc_co_u32_e64 v235, s[18:19], 0, v235, s[16:17]
	v_cmp_ge_f32_e64 s[16:17], v202, v35
	v_addc_co_u32_e64 v235, s[18:19], 0, v235, s[12:13]
	v_cmp_ge_f32_e64 s[12:13], v203, v35
	v_addc_co_u32_e64 v235, s[18:19], 0, v235, s[14:15]
	v_cmp_ge_f32_e64 s[14:15], v204, v35
	v_addc_co_u32_e64 v235, s[18:19], 0, v235, s[16:17]
	v_cmp_ge_f32_e64 s[16:17], v205, v35
	v_addc_co_u32_e64 v235, s[18:19], 0, v235, s[12:13]
	v_cmp_ge_f32_e64 s[12:13], v206, v35
	v_addc_co_u32_e64 v235, s[18:19], 0, v235, s[14:15]
	v_cmp_ge_f32_e64 s[14:15], v207, v35
	v_addc_co_u32_e64 v235, s[18:19], 0, v235, s[16:17]
	v_cmp_ge_f32_e64 s[16:17], v208, v35
	v_addc_co_u32_e64 v235, s[18:19], 0, v235, s[12:13]
	v_cmp_ge_f32_e64 s[12:13], v209, v35
	v_addc_co_u32_e64 v235, s[18:19], 0, v235, s[14:15]
	v_cmp_ge_f32_e64 s[14:15], v210, v35
	v_addc_co_u32_e64 v235, s[18:19], 0, v235, s[16:17]
	v_cmp_ge_f32_e64 s[16:17], v211, v35
	v_addc_co_u32_e64 v235, s[18:19], 0, v235, s[12:13]
	v_cmp_ge_f32_e64 s[12:13], v212, v35
	v_addc_co_u32_e64 v235, s[18:19], 0, v235, s[14:15]
	v_cmp_ge_f32_e64 s[14:15], v213, v35
	v_addc_co_u32_e64 v235, s[18:19], 0, v235, s[16:17]
	v_cmp_ge_f32_e64 s[16:17], v214, v35
	v_addc_co_u32_e64 v235, s[18:19], 0, v235, s[12:13]
	v_cmp_ge_f32_e64 s[12:13], v215, v35
	v_addc_co_u32_e64 v235, s[18:19], 0, v235, s[14:15]
	v_cmp_ge_f32_e64 s[14:15], v216, v35
	v_addc_co_u32_e64 v235, s[18:19], 0, v235, s[16:17]
	v_cmp_ge_f32_e64 s[16:17], v217, v35
	v_addc_co_u32_e64 v235, s[18:19], 0, v235, s[12:13]
	v_cmp_gt_f32_e64 s[12:13], v218, v35
	v_cmp_ge_f32_e64 s[20:21], v218, v35
	s_and_b64 s[20:21], s[20:21], s[6:7]
	s_or_b64 s[12:13], s[12:13], s[20:21]
	v_addc_co_u32_e64 v235, s[18:19], 0, v235, s[14:15]
	v_cmp_gt_f32_e64 s[14:15], v219, v35
	v_cmp_ge_f32_e64 s[20:21], v219, v35
	s_and_b64 s[20:21], s[20:21], s[8:9]
	s_or_b64 s[14:15], s[14:15], s[20:21]
	v_addc_co_u32_e64 v235, s[18:19], 0, v235, s[16:17]
	v_cmp_gt_f32_e64 s[16:17], v220, v35
	v_cmp_ge_f32_e64 s[20:21], v220, v35
	s_and_b64 s[20:21], s[20:21], s[10:11]
	s_or_b64 s[16:17], s[16:17], s[20:21]
	v_addc_co_u32_e64 v235, s[18:19], 0, v235, s[12:13]
	v_cmp_gt_f32_e64 s[12:13], v221, v35
	v_addc_co_u32_e64 v235, s[18:19], 0, v235, s[14:15]
	v_cmp_gt_f32_e64 s[14:15], v222, v35
	v_addc_co_u32_e64 v235, s[18:19], 0, v235, s[16:17]
	v_cmp_gt_f32_e64 s[16:17], v223, v35
	v_addc_co_u32_e64 v235, s[18:19], 0, v235, s[12:13]
	v_cmp_gt_f32_e64 s[12:13], v224, v35
	v_addc_co_u32_e64 v235, s[18:19], 0, v235, s[14:15]
	v_cmp_gt_f32_e64 s[14:15], v225, v35
	v_addc_co_u32_e64 v235, s[18:19], 0, v235, s[16:17]
	v_cmp_gt_f32_e64 s[16:17], v226, v35
	v_addc_co_u32_e64 v235, s[18:19], 0, v235, s[12:13]
	v_cmp_gt_f32_e64 s[12:13], v227, v35
	v_addc_co_u32_e64 v235, s[18:19], 0, v235, s[14:15]
	v_cmp_gt_f32_e64 s[14:15], v228, v35
	v_addc_co_u32_e64 v235, s[18:19], 0, v235, s[16:17]
	v_cmp_gt_f32_e64 s[16:17], v229, v35
	v_addc_co_u32_e64 v235, s[18:19], 0, v235, s[12:13]
	v_cmp_ge_f32_e64 s[12:13], v198, v34
	v_addc_co_u32_e64 v235, s[18:19], 0, v235, s[14:15]
	v_cmp_ge_f32_e64 s[14:15], v199, v34
	v_addc_co_u32_e64 v235, s[18:19], 0, v235, s[16:17]
	v_cmp_ge_f32_e64 s[16:17], v200, v34
	v_addc_co_u32_e64 v236, s[18:19], 0, v236, s[12:13]
	v_cmp_ge_f32_e64 s[12:13], v201, v34
	v_addc_co_u32_e64 v236, s[18:19], 0, v236, s[14:15]
	v_cmp_ge_f32_e64 s[14:15], v202, v34
	v_addc_co_u32_e64 v236, s[18:19], 0, v236, s[16:17]
	v_cmp_ge_f32_e64 s[16:17], v203, v34
	v_addc_co_u32_e64 v236, s[18:19], 0, v236, s[12:13]
	v_cmp_ge_f32_e64 s[12:13], v204, v34
	v_addc_co_u32_e64 v236, s[18:19], 0, v236, s[14:15]
	v_cmp_ge_f32_e64 s[14:15], v205, v34
	v_addc_co_u32_e64 v236, s[18:19], 0, v236, s[16:17]
	v_cmp_ge_f32_e64 s[16:17], v206, v34
	v_addc_co_u32_e64 v236, s[18:19], 0, v236, s[12:13]
	v_cmp_ge_f32_e64 s[12:13], v207, v34
	v_addc_co_u32_e64 v236, s[18:19], 0, v236, s[14:15]
	v_cmp_ge_f32_e64 s[14:15], v208, v34
	v_addc_co_u32_e64 v236, s[18:19], 0, v236, s[16:17]
	v_cmp_ge_f32_e64 s[16:17], v209, v34
	v_addc_co_u32_e64 v236, s[18:19], 0, v236, s[12:13]
	v_cmp_ge_f32_e64 s[12:13], v210, v34
	v_addc_co_u32_e64 v236, s[18:19], 0, v236, s[14:15]
	v_cmp_ge_f32_e64 s[14:15], v211, v34
	v_addc_co_u32_e64 v236, s[18:19], 0, v236, s[16:17]
	v_cmp_ge_f32_e64 s[16:17], v212, v34
	v_addc_co_u32_e64 v236, s[18:19], 0, v236, s[12:13]
	v_cmp_ge_f32_e64 s[12:13], v213, v34
	v_addc_co_u32_e64 v236, s[18:19], 0, v236, s[14:15]
	v_cmp_ge_f32_e64 s[14:15], v214, v34
	v_addc_co_u32_e64 v236, s[18:19], 0, v236, s[16:17]
	v_cmp_ge_f32_e64 s[16:17], v215, v34
	v_addc_co_u32_e64 v236, s[18:19], 0, v236, s[12:13]
	v_cmp_ge_f32_e64 s[12:13], v216, v34
	v_addc_co_u32_e64 v236, s[18:19], 0, v236, s[14:15]
	v_cmp_ge_f32_e64 s[14:15], v217, v34
	v_addc_co_u32_e64 v236, s[18:19], 0, v236, s[16:17]
	v_cmp_ge_f32_e64 s[16:17], v218, v34
	v_addc_co_u32_e64 v236, s[18:19], 0, v236, s[12:13]
	v_cmp_ge_f32_e64 s[12:13], v219, v34
	v_addc_co_u32_e64 v236, s[18:19], 0, v236, s[14:15]
	v_cmp_ge_f32_e64 s[14:15], v220, v34
	v_addc_co_u32_e64 v236, s[18:19], 0, v236, s[16:17]
	v_cmp_ge_f32_e64 s[16:17], v221, v34
	v_addc_co_u32_e64 v236, s[18:19], 0, v236, s[12:13]
	v_cmp_gt_f32_e64 s[12:13], v222, v34
	v_cmp_ge_f32_e64 s[20:21], v222, v34
	s_and_b64 s[20:21], s[20:21], s[6:7]
	s_or_b64 s[12:13], s[12:13], s[20:21]
	v_addc_co_u32_e64 v236, s[18:19], 0, v236, s[14:15]
	v_cmp_gt_f32_e64 s[14:15], v223, v34
	v_cmp_ge_f32_e64 s[20:21], v223, v34
; DI int lane_get_i(int v, int srclane) { return __builtin_amdgcn_ds_bpermute(srclane << 2, v); }
; DI void attn_phase(const Params& p, const int layer, const int wid_s) {
;     ...
; #pragma unroll
;         for (int nt = 0; nt < 8; ++nt) {
;           const float a = impv[nt]; const int ja = nt * 4 + fql;
; #pragma unroll
;           for (int c = 0; c < 4; ++c) cnt[nt] += (int)(rv[c] > a) | ((int)(rv[c] == a) & (int)((4 * i + c) < ja));
;         }
;       }
;       mk = 0;
; #pragma unroll
;       for (int nt = 0; nt < 8; ++nt) { const int ja = nt * 4 + fql; if (cnt[nt] < 8 && ja <= cur) mk |= 1u << ja; }
;       mk |= (unsigned)lane_get_i((int)mk, lane ^ 16);
;       mk |= (unsigned)lane_get_i((int)mk, lane ^ 32);
	s_and_b64 s[20:21], s[20:21], s[8:9]
	s_or_b64 s[14:15], s[14:15], s[20:21]
	v_addc_co_u32_e64 v236, s[18:19], 0, v236, s[16:17]
	v_cmp_gt_f32_e64 s[16:17], v224, v34
	v_cmp_ge_f32_e64 s[20:21], v224, v34
	s_and_b64 s[20:21], s[20:21], s[10:11]
	s_or_b64 s[16:17], s[16:17], s[20:21]
	v_addc_co_u32_e64 v236, s[18:19], 0, v236, s[12:13]
	v_cmp_gt_f32_e64 s[12:13], v225, v34
	v_addc_co_u32_e64 v236, s[18:19], 0, v236, s[14:15]
	v_cmp_gt_f32_e64 s[14:15], v226, v34
	v_addc_co_u32_e64 v236, s[18:19], 0, v236, s[16:17]
	v_cmp_gt_f32_e64 s[16:17], v227, v34
	v_addc_co_u32_e64 v236, s[18:19], 0, v236, s[12:13]
	v_cmp_gt_f32_e64 s[12:13], v228, v34
	v_addc_co_u32_e64 v236, s[18:19], 0, v236, s[14:15]
	v_cmp_gt_f32_e64 s[14:15], v229, v34
	v_addc_co_u32_e64 v236, s[18:19], 0, v236, s[16:17]
	v_cmp_ge_f32_e64 s[16:17], v198, v33
	v_addc_co_u32_e64 v236, s[18:19], 0, v236, s[12:13]
	v_cmp_ge_f32_e64 s[12:13], v199, v33
	v_addc_co_u32_e64 v236, s[18:19], 0, v236, s[14:15]
	v_cmp_ge_f32_e64 s[14:15], v200, v33
	v_addc_co_u32_e64 v237, s[18:19], 0, v237, s[16:17]
	v_cmp_ge_f32_e64 s[16:17], v201, v33
	v_addc_co_u32_e64 v237, s[18:19], 0, v237, s[12:13]
	v_cmp_ge_f32_e64 s[12:13], v202, v33
	v_addc_co_u32_e64 v237, s[18:19], 0, v237, s[14:15]
	v_cmp_ge_f32_e64 s[14:15], v203, v33
	v_addc_co_u32_e64 v237, s[18:19], 0, v237, s[16:17]
	v_cmp_ge_f32_e64 s[16:17], v204, v33
	v_addc_co_u32_e64 v237, s[18:19], 0, v237, s[12:13]
	v_cmp_ge_f32_e64 s[12:13], v205, v33
	v_addc_co_u32_e64 v237, s[18:19], 0, v237, s[14:15]
	v_cmp_ge_f32_e64 s[14:15], v206, v33
	v_addc_co_u32_e64 v237, s[18:19], 0, v237, s[16:17]
	v_cmp_ge_f32_e64 s[16:17], v207, v33
	v_addc_co_u32_e64 v237, s[18:19], 0, v237, s[12:13]
	v_cmp_ge_f32_e64 s[12:13], v208, v33
	v_addc_co_u32_e64 v237, s[18:19], 0, v237, s[14:15]
	v_cmp_ge_f32_e64 s[14:15], v209, v33
	v_addc_co_u32_e64 v237, s[18:19], 0, v237, s[16:17]
	v_cmp_ge_f32_e64 s[16:17], v210, v33
	v_addc_co_u32_e64 v237, s[18:19], 0, v237, s[12:13]
	v_cmp_ge_f32_e64 s[12:13], v211, v33
	v_addc_co_u32_e64 v237, s[18:19], 0, v237, s[14:15]
	v_cmp_ge_f32_e64 s[14:15], v212, v33
	v_addc_co_u32_e64 v237, s[18:19], 0, v237, s[16:17]
	v_cmp_ge_f32_e64 s[16:17], v213, v33
	v_addc_co_u32_e64 v237, s[18:19], 0, v237, s[12:13]
	v_cmp_ge_f32_e64 s[12:13], v214, v33
	v_addc_co_u32_e64 v237, s[18:19], 0, v237, s[14:15]
	v_cmp_ge_f32_e64 s[14:15], v215, v33
	v_addc_co_u32_e64 v237, s[18:19], 0, v237, s[16:17]
	v_cmp_ge_f32_e64 s[16:17], v216, v33
	v_addc_co_u32_e64 v237, s[18:19], 0, v237, s[12:13]
	v_cmp_ge_f32_e64 s[12:13], v217, v33
	v_addc_co_u32_e64 v237, s[18:19], 0, v237, s[14:15]
	v_cmp_ge_f32_e64 s[14:15], v218, v33
	v_addc_co_u32_e64 v237, s[18:19], 0, v237, s[16:17]
	v_cmp_ge_f32_e64 s[16:17], v219, v33
	v_addc_co_u32_e64 v237, s[18:19], 0, v237, s[12:13]
	v_cmp_ge_f32_e64 s[12:13], v220, v33
	v_addc_co_u32_e64 v237, s[18:19], 0, v237, s[14:15]
	v_cmp_ge_f32_e64 s[14:15], v221, v33
	v_addc_co_u32_e64 v237, s[18:19], 0, v237, s[16:17]
	v_cmp_ge_f32_e64 s[16:17], v222, v33
	v_addc_co_u32_e64 v237, s[18:19], 0, v237, s[12:13]
	v_cmp_ge_f32_e64 s[12:13], v223, v33
	v_addc_co_u32_e64 v237, s[18:19], 0, v237, s[14:15]
	v_cmp_ge_f32_e64 s[14:15], v224, v33
	v_addc_co_u32_e64 v237, s[18:19], 0, v237, s[16:17]
	v_cmp_ge_f32_e64 s[16:17], v225, v33
	v_addc_co_u32_e64 v237, s[18:19], 0, v237, s[12:13]
	v_cmp_gt_f32_e64 s[12:13], v226, v33
	v_cmp_ge_f32_e64 s[20:21], v226, v33
	s_and_b64 s[20:21], s[20:21], s[6:7]
	s_or_b64 s[12:13], s[12:13], s[20:21]
	v_addc_co_u32_e64 v237, s[18:19], 0, v237, s[14:15]
	v_cmp_gt_f32_e64 s[14:15], v227, v33
	v_cmp_ge_f32_e64 s[20:21], v227, v33
	s_and_b64 s[20:21], s[20:21], s[8:9]
	s_or_b64 s[14:15], s[14:15], s[20:21]
	v_addc_co_u32_e64 v237, s[18:19], 0, v237, s[16:17]
	v_cmp_gt_f32_e64 s[16:17], v228, v33
	v_cmp_ge_f32_e64 s[20:21], v228, v33
	s_and_b64 s[20:21], s[20:21], s[10:11]
	s_or_b64 s[16:17], s[16:17], s[20:21]
	v_addc_co_u32_e64 v237, s[18:19], 0, v237, s[12:13]
	v_cmp_gt_f32_e64 s[12:13], v229, v33
	v_addc_co_u32_e64 v237, s[18:19], 0, v237, s[14:15]
	s_nop 1
	v_addc_co_u32_e64 v237, s[18:19], 0, v237, s[16:17]
	v_addc_co_u32_e64 v237, s[18:19], 0, v237, s[12:13]
	v_cmp_gt_u32_e64 s[12:13], 8, v230
	v_cmp_ge_i32_e64 s[14:15], s54, v238
	v_lshlrev_b32_e64 v238, v238, 1
	s_and_b64 s[12:13], s[12:13], s[14:15]
	s_nop 1
	v_cndmask_b32_e64 v238, 0, v238, s[12:13]
	v_cmp_gt_u32_e64 s[16:17], 8, v231
	v_cmp_ge_i32_e64 s[20:21], s54, v239
	v_lshlrev_b32_e64 v239, v239, 1
	s_and_b64 s[16:17], s[16:17], s[20:21]
	s_nop 1
	v_cndmask_b32_e64 v239, 0, v239, s[16:17]
	v_cmp_gt_u32_e64 s[12:13], 8, v232
	v_cmp_ge_i32_e64 s[14:15], s54, v240
	v_lshlrev_b32_e64 v240, v240, 1
	s_and_b64 s[12:13], s[12:13], s[14:15]
	s_nop 1
	v_cndmask_b32_e64 v240, 0, v240, s[12:13]
	v_cmp_gt_u32_e64 s[16:17], 8, v233
	v_cmp_ge_i32_e64 s[20:21], s54, v241
	v_lshlrev_b32_e64 v241, v241, 1
	s_and_b64 s[16:17], s[16:17], s[20:21]
	s_nop 1
	v_cndmask_b32_e64 v241, 0, v241, s[16:17]
	v_cmp_gt_u32_e64 s[12:13], 8, v234
	v_cmp_ge_i32_e64 s[14:15], s54, v242
	v_lshlrev_b32_e64 v242, v242, 1
	s_and_b64 s[12:13], s[12:13], s[14:15]
	s_nop 1
	v_cndmask_b32_e64 v242, 0, v242, s[12:13]
	v_cmp_gt_u32_e64 s[16:17], 8, v235
	v_cmp_ge_i32_e64 s[20:21], s54, v243
	v_lshlrev_b32_e64 v243, v243, 1
	s_and_b64 s[16:17], s[16:17], s[20:21]
	s_nop 1
	v_cndmask_b32_e64 v243, 0, v243, s[16:17]
	v_cmp_gt_u32_e64 s[12:13], 8, v236
	v_cmp_ge_i32_e64 s[14:15], s54, v244
	v_lshlrev_b32_e64 v244, v244, 1
	s_and_b64 s[12:13], s[12:13], s[14:15]
	s_nop 1
	v_cndmask_b32_e64 v244, 0, v244, s[12:13]
	v_cmp_gt_u32_e64 s[16:17], 8, v237
	v_cmp_ge_i32_e64 s[20:21], s54, v245
	v_lshlrev_b32_e64 v245, v245, 1
	s_and_b64 s[16:17], s[16:17], s[20:21]
	s_nop 1
	v_cndmask_b32_e64 v245, 0, v245, s[16:17]
	v_or3_b32 v0, v238, v239, v240
	v_or3_b32 v2, v241, v242, v243
	v_or3_b32 v0, v0, v244, v245
	v_or_b32_e32 v0, v0, v2
	v_mov_b32_e32 v2, v0
	s_waitcnt lgkmcnt(0)
	s_nop 1
	v_permlane16_swap_b32_e32 v2, v0
	v_or_b32_e32 v0, v0, v2
	v_mov_b32_e32 v2, v0
	s_waitcnt lgkmcnt(0)
	s_nop 1
	v_permlane32_swap_b32_e32 v2, v0
	v_or_b32_e32 v5, v0, v2
; DI float red4_sum(float v, int lane) { v += lane_get(v, lane ^ 16); v += lane_get(v, lane ^ 32); return v; }
; DI void attn_phase(const Params& p, const int layer, const int wid_s) {
;     ...
;       for (int br = 0; br < 3; ++br) {
;         const float gl = (float)hb[(size_t)t * LDH + C_GL + (hh0 + hp) * 3 + br];
;         gate[hp][br] = 1.f / (1.f + __expf(-gl));
;     ...
;       const float* kmx = (const float*)(p.ws + OFF_KMAX) + layer * 128;
;       const float k2s = kmx[bg], k2w = kmx[64 + bg];
; #pragma unroll
;       for (int hp = 0; hp < 2; ++hp) {
;         float q2 = 0.f;
; #pragma unroll
;         for (int ks = 0; ks < 2; ++ks)
; #pragma unroll
;           for (int j = 0; j < 8; ++j) q2 += (float)q[hp][ks][j] * (float)q[hp][ks][j];
;         q2 = red4_sum(q2, lane);
;         const float bm = tabh[hp * 132 + 129];
;         nRs[hp] = 12.f - (sqrtf(q2 * k2s) * 1.002f + 0.01f + bm);
;         nRw[hp] = 12.f - (sqrtf(q2 * k2w) * 1.002f + 0.01f + bm);
.LBB0_334:
	s_andn2_b64 vcc, exec, s[70:71]
	s_mov_b32 s54, 0xf800
	s_cbranch_vccnz .LBB0_191
	v_cvt_f32_f16_sdwa v0, v120 dst_sel:DWORD dst_unused:UNUSED_PAD src0_sel:WORD_1
	v_readlane_b32 s4, v249, 37
	v_readlane_b32 s5, v249, 38
	v_add_u32_e32 v195, s50, v186
	v_mul_f32_e32 v0, 0xbfb8aa3b, v0
	v_exp_f32_e32 v0, v0
	s_nop 0
	v_add_f32_e32 v0, 1.0, v0
	v_div_scale_f32 v2, s[0:1], v0, v0, 1.0
	v_rcp_f32_e32 v3, v2
	s_nop 0
	v_fma_f32 v6, -v2, v3, 1.0
	v_fmac_f32_e32 v3, v6, v3
	v_div_scale_f32 v6, vcc, 1.0, v0, 1.0
	v_mul_f32_e32 v7, v6, v3
	v_fma_f32 v24, -v2, v7, v6
	v_fmac_f32_e32 v7, v24, v3
	v_fma_f32 v2, -v2, v7, v6
	v_div_fmas_f32 v2, v2, v3, v7
	v_div_fixup_f32 v189, v2, v0, 1.0
	v_cvt_f32_f16_e32 v0, v121
	v_mul_f32_e32 v0, 0xbfb8aa3b, v0
	v_exp_f32_e32 v0, v0
	s_nop 0
	v_add_f32_e32 v0, 1.0, v0
	v_div_scale_f32 v2, s[0:1], v0, v0, 1.0
	v_rcp_f32_e32 v3, v2
	s_nop 0
	v_fma_f32 v6, -v2, v3, 1.0
	v_fmac_f32_e32 v3, v6, v3
	v_div_scale_f32 v6, vcc, 1.0, v0, 1.0
	v_mul_f32_e32 v7, v6, v3
	v_fma_f32 v24, -v2, v7, v6
	v_fmac_f32_e32 v7, v24, v3
	v_fma_f32 v2, -v2, v7, v6
	v_div_fmas_f32 v2, v2, v3, v7
	v_div_fixup_f32 v190, v2, v0, 1.0
	v_cvt_f32_f16_e32 v0, v122
	v_mul_f32_e32 v0, 0xbfb8aa3b, v0
	v_exp_f32_e32 v0, v0
	s_nop 0
	v_add_f32_e32 v0, 1.0, v0
	v_div_scale_f32 v2, s[0:1], v0, v0, 1.0
	v_rcp_f32_e32 v3, v2
	s_nop 0
	v_fma_f32 v6, -v2, v3, 1.0
	v_fmac_f32_e32 v3, v6, v3
	v_div_scale_f32 v6, vcc, 1.0, v0, 1.0
	v_mul_f32_e32 v7, v6, v3
	v_fma_f32 v24, -v2, v7, v6
	v_fmac_f32_e32 v7, v24, v3
	v_fma_f32 v2, -v2, v7, v6
	v_div_fmas_f32 v2, v2, v3, v7
	v_div_fixup_f32 v191, v2, v0, 1.0
	v_cvt_f32_f16_sdwa v0, v122 dst_sel:DWORD dst_unused:UNUSED_PAD src0_sel:WORD_1
	v_mul_f32_e32 v0, 0xbfb8aa3b, v0
	v_exp_f32_e32 v0, v0
	s_nop 0
	v_add_f32_e32 v0, 1.0, v0
	v_div_scale_f32 v2, s[0:1], v0, v0, 1.0
	v_rcp_f32_e32 v3, v2
	s_lshl_b64 s[0:1], s[52:53], 2
	s_add_u32 s0, s4, s0
	s_addc_u32 s1, s5, s1
	v_fma_f32 v6, -v2, v3, 1.0
	v_fmac_f32_e32 v3, v6, v3
	v_div_scale_f32 v6, vcc, 1.0, v0, 1.0
	v_mul_f32_e32 v7, v6, v3
	v_fma_f32 v24, -v2, v7, v6
	v_fmac_f32_e32 v7, v24, v3
	v_fma_f32 v2, -v2, v7, v6
	v_div_fmas_f32 v2, v2, v3, v7
	v_div_fixup_f32 v192, v2, v0, 1.0
	v_mov_b64_e32 v[2:3], s[0:1]
	flat_load_dword v0, v[2:3]
	flat_load_dword v6, v[2:3] offset:256
	v_cvt_f32_f16_sdwa v2, v8 dst_sel:DWORD dst_unused:UNUSED_PAD src0_sel:WORD_1
	s_mov_b32 s4, 0xf800000
	s_or_b32 s14, s50, 32
	s_and_b32 s15, s51, 0xffffffe0
	v_mul_f32_e32 v2, v2, v2
	v_fma_mix_f32 v2, v8, v8, v2 op_sel_hi:[1,1,0]
	s_nop 0
	v_fma_mix_f32 v2, v9, v9, v2 op_sel_hi:[1,1,0]
	s_nop 0
	v_fma_mix_f32 v2, v9, v9, v2 op_sel:[1,1,0] op_sel_hi:[1,1,0]
	s_nop 0
	v_fma_mix_f32 v2, v10, v10, v2 op_sel_hi:[1,1,0]
	s_nop 0
	v_fma_mix_f32 v2, v10, v10, v2 op_sel:[1,1,0] op_sel_hi:[1,1,0]
	s_nop 0
	v_fma_mix_f32 v2, v11, v11, v2 op_sel_hi:[1,1,0]
	s_nop 0
	v_fma_mix_f32 v2, v11, v11, v2 op_sel:[1,1,0] op_sel_hi:[1,1,0]
	s_nop 0
	v_fma_mix_f32 v2, v12, v12, v2 op_sel_hi:[1,1,0]
	s_nop 0
	v_fma_mix_f32 v2, v12, v12, v2 op_sel:[1,1,0] op_sel_hi:[1,1,0]
	s_nop 0
	v_fma_mix_f32 v2, v13, v13, v2 op_sel_hi:[1,1,0]
	s_nop 0
	v_fma_mix_f32 v2, v13, v13, v2 op_sel:[1,1,0] op_sel_hi:[1,1,0]
	s_nop 0
	v_fma_mix_f32 v2, v14, v14, v2 op_sel_hi:[1,1,0]
	s_nop 0
	v_fma_mix_f32 v2, v14, v14, v2 op_sel:[1,1,0] op_sel_hi:[1,1,0]
	s_nop 0
	v_fma_mix_f32 v2, v15, v15, v2 op_sel_hi:[1,1,0]
	s_nop 0
	v_fma_mix_f32 v2, v15, v15, v2 op_sel:[1,1,0] op_sel_hi:[1,1,0]
	v_mov_b32_e32 v3, v2
	s_waitcnt lgkmcnt(0)
	s_nop 1
	v_permlane16_swap_b32_e32 v3, v2
	v_add_f32_e32 v2, v2, v3
	v_mov_b32_e32 v3, v2
	s_waitcnt lgkmcnt(0)
	s_nop 1
	v_permlane32_swap_b32_e32 v3, v2
	v_add_f32_e32 v7, v2, v3
	v_mov_b32_e32 v2, s38
	v_add_u32_e32 v2, 0x200, v2
	ds_read2_b32 v[2:3], v2 offset0:1 offset1:133
	s_waitcnt vmcnt(0)
	v_mul_f32_e32 v24, v0, v7
	v_cmp_gt_f32_e32 vcc, s4, v24
	v_mul_f32_e32 v25, 0x4f800000, v24
	v_mul_f32_e32 v7, v6, v7
	v_cndmask_b32_e32 v24, v24, v25, vcc
	v_sqrt_f32_e32 v25, v24
	s_nop 0
	v_add_u32_e32 v26, -1, v25
	v_fma_f32 v27, -v26, v25, v24
	v_cmp_ge_f32_e64 s[0:1], 0, v27
	v_add_u32_e32 v27, 1, v25
	s_nop 0
	v_cndmask_b32_e64 v26, v25, v26, s[0:1]
	v_fma_f32 v25, -v27, v25, v24
	v_cmp_lt_f32_e64 s[0:1], 0, v25
	s_nop 1
	v_cndmask_b32_e64 v25, v26, v27, s[0:1]
	v_mul_f32_e32 v26, 0x37800000, v25
	v_cndmask_b32_e32 v25, v25, v26, vcc
	v_cmp_class_f32_e32 vcc, v24, v149
	s_nop 1
	v_cndmask_b32_e32 v24, v25, v24, vcc
	v_fmamk_f32 v24, v24, 0x3f804189, v156
	s_waitcnt lgkmcnt(0)
; #define LAS __attribute__((address_space(3)))
; DI float red4_sum(float v, int lane) { v += lane_get(v, lane ^ 16); v += lane_get(v, lane ^ 32); return v; }
; DI void attn_phase(const Params& p, const int layer, const int wid_s) {
;     ...
;       for (int hp = 0; hp < 2; ++hp) {
;         float q2 = 0.f;
; #pragma unroll
;         for (int ks = 0; ks < 2; ++ks)
; #pragma unroll
;           for (int j = 0; j < 8; ++j) q2 += (float)q[hp][ks][j] * (float)q[hp][ks][j];
;         q2 = red4_sum(q2, lane);
;         const float bm = tabh[hp * 132 + 129];
;         nRs[hp] = 12.f - (sqrtf(q2 * k2s) * 1.002f + 0.01f + bm);
;         nRw[hp] = 12.f - (sqrtf(q2 * k2w) * 1.002f + 0.01f + bm);
;       }
;     }
;     {
;       LAS unsigned char* ring = (LAS unsigned char*)smem + 104576;
;       int k_src_off, v_src_off;
;       { const int r = tid >> 3, cs = tid & 7, c = cs ^ (r & 7); k_src_off = r * LDH + c * 8; }
;       { const int i = tid & 255, r = i >> 2, cs = i & 3, c = cs ^ ((r >> 2) & 3); v_src_off = r * 32 + c * 8; }
;       const unsigned stage_dst = (unsigned)(wave < 4 ? wave * 1024 : 4096 + (wave - 4) * 1024);
;       unsigned kread[2][2], vread[4];
; #pragma unroll
;       for (int kt = 0; kt < 2; ++kt)
; #pragma unroll
;         for (int ks = 0; ks < 2; ++ks) { const int r = kt * 16 + fr, c = ks * 4 + fq; kread[kt][ks] = (unsigned)(r * 128 + ((c ^ (r & 7)) * 16)); }
; #pragma unroll
;       for (int dt = 0; dt < 4; ++dt) { const int r = dt * 16 + fr; vread[dt] = (unsigned)(4096 + r * 64 + ((fq ^ ((r >> 2) & 3)) * 16)); }
;       const int kb_last = qblk * 64 + 32;
;       const int kmax_w = (t0 + 15) & ~31;
; #pragma unroll 1
;       for (int br = 1; br <= 2; ++br) {
;         const h16* kbase = hb + (br == 1 ? C_KS : C_KW) + g * 64;
;         const h16* vT = (const h16*)(p.ws + (br == 1 ? OFF_VST : OFF_VWT)) + (size_t)bg * 64 * SEQ;
;         int kb0 = 0, lo_w = 0;
;         if (br == 2) { kb0 = qblk * 64 - 512; if (kb0 < 0) kb0 = 0; lo_w = t0 - 511; if (lo_w < 0) lo_w = 0; lo_w &= ~31; }
	v_add_f32_e32 v24, v2, v24
	v_sub_f32_e32 v193, 0x41400000, v24
	v_cmp_gt_f32_e32 vcc, s4, v7
	v_mul_f32_e32 v24, 0x4f800000, v7
	s_nop 0
	v_cndmask_b32_e32 v7, v7, v24, vcc
	v_sqrt_f32_e32 v24, v7
	s_nop 0
	v_add_u32_e32 v25, -1, v24
	v_fma_f32 v26, -v25, v24, v7
	v_cmp_ge_f32_e64 s[0:1], 0, v26
	v_add_u32_e32 v26, 1, v24
	s_nop 0
	v_cndmask_b32_e64 v25, v24, v25, s[0:1]
	v_fma_f32 v24, -v26, v24, v7
	v_cmp_lt_f32_e64 s[0:1], 0, v24
	s_nop 1
	v_cndmask_b32_e64 v24, v25, v26, s[0:1]
	v_mul_f32_e32 v25, 0x37800000, v24
	v_cndmask_b32_e32 v24, v24, v25, vcc
	v_cmp_class_f32_e32 vcc, v7, v149
	s_nop 1
	v_cndmask_b32_e32 v7, v24, v7, vcc
	v_fmamk_f32 v7, v7, 0x3f804189, v156
	v_add_f32_e32 v2, v2, v7
	v_sub_f32_e32 v24, 0x41400000, v2
	v_cvt_f32_f16_sdwa v2, v16 dst_sel:DWORD dst_unused:UNUSED_PAD src0_sel:WORD_1
	v_mov_b32_e32 v27, v24
	v_mul_f32_e32 v2, v2, v2
	v_fma_mix_f32 v2, v16, v16, v2 op_sel_hi:[1,1,0]
	s_nop 0
	v_fma_mix_f32 v2, v17, v17, v2 op_sel_hi:[1,1,0]
	s_nop 0
	v_fma_mix_f32 v2, v17, v17, v2 op_sel:[1,1,0] op_sel_hi:[1,1,0]
	s_nop 0
	v_fma_mix_f32 v2, v18, v18, v2 op_sel_hi:[1,1,0]
	s_nop 0
	v_fma_mix_f32 v2, v18, v18, v2 op_sel:[1,1,0] op_sel_hi:[1,1,0]
	s_nop 0
	v_fma_mix_f32 v2, v19, v19, v2 op_sel_hi:[1,1,0]
	s_nop 0
	v_fma_mix_f32 v2, v19, v19, v2 op_sel:[1,1,0] op_sel_hi:[1,1,0]
	s_nop 0
	v_fma_mix_f32 v2, v20, v20, v2 op_sel_hi:[1,1,0]
	s_nop 0
	v_fma_mix_f32 v2, v20, v20, v2 op_sel:[1,1,0] op_sel_hi:[1,1,0]
	s_nop 0
	v_fma_mix_f32 v2, v21, v21, v2 op_sel_hi:[1,1,0]
	s_nop 0
	v_fma_mix_f32 v2, v21, v21, v2 op_sel:[1,1,0] op_sel_hi:[1,1,0]
	s_nop 0
	v_fma_mix_f32 v2, v22, v22, v2 op_sel_hi:[1,1,0]
	s_nop 0
	v_fma_mix_f32 v2, v22, v22, v2 op_sel:[1,1,0] op_sel_hi:[1,1,0]
	s_nop 0
	v_fma_mix_f32 v2, v23, v23, v2 op_sel_hi:[1,1,0]
	s_nop 0
	v_fma_mix_f32 v2, v23, v23, v2 op_sel:[1,1,0] op_sel_hi:[1,1,0]
	v_mov_b32_e32 v7, v2
	s_waitcnt lgkmcnt(0)
	s_nop 1
	v_permlane16_swap_b32_e32 v7, v2
	v_add_f32_e32 v2, v2, v7
	v_mov_b32_e32 v7, v2
	s_waitcnt lgkmcnt(0)
	s_nop 1
	v_permlane32_swap_b32_e32 v7, v2
	v_add_f32_e32 v2, v2, v7
	v_mul_f32_e32 v0, v0, v2
	v_cmp_gt_f32_e32 vcc, s4, v0
	v_mul_f32_e32 v7, 0x4f800000, v0
	s_nop 0
	v_cndmask_b32_e32 v0, v0, v7, vcc
	v_sqrt_f32_e32 v7, v0
	s_nop 0
	v_add_u32_e32 v25, -1, v7
	v_fma_f32 v26, -v25, v7, v0
	v_cmp_ge_f32_e64 s[0:1], 0, v26
	v_add_u32_e32 v26, 1, v7
	s_nop 0
	v_cndmask_b32_e64 v25, v7, v25, s[0:1]
	v_fma_f32 v7, -v26, v7, v0
	v_cmp_lt_f32_e64 s[0:1], 0, v7
	s_nop 1
	v_cndmask_b32_e64 v7, v25, v26, s[0:1]
	v_mul_f32_e32 v25, 0x37800000, v7
	v_cndmask_b32_e32 v7, v7, v25, vcc
	v_cmp_class_f32_e32 vcc, v0, v149
	v_mov_b32_e32 v25, v24
	v_mov_b32_e32 v26, v24
	v_cndmask_b32_e32 v0, v7, v0, vcc
	v_fmamk_f32 v0, v0, 0x3f804189, v156
	v_add_f32_e32 v0, v3, v0
	v_sub_f32_e32 v194, 0x41400000, v0
	v_mul_f32_e32 v0, v6, v2
	v_cmp_gt_f32_e32 vcc, s4, v0
	v_mul_f32_e32 v2, 0x4f800000, v0
	s_mov_b64 s[4:5], 0
	v_cndmask_b32_e32 v0, v0, v2, vcc
	v_sqrt_f32_e32 v2, v0
	s_nop 0
	v_add_u32_e32 v6, -1, v2
	v_fma_f32 v7, -v6, v2, v0
	v_cmp_ge_f32_e64 s[0:1], 0, v7
	v_add_u32_e32 v7, 1, v2
	s_nop 0
	v_cndmask_b32_e64 v6, v2, v6, s[0:1]
	v_fma_f32 v2, -v7, v2, v0
	v_cmp_lt_f32_e64 s[0:1], 0, v2
	s_nop 1
	v_cndmask_b32_e64 v2, v6, v7, s[0:1]
	s_lshl_b32 s0, s39, 7
	s_add_u32 s16, s68, s0
	v_mul_f32_e32 v6, 0x37800000, v2
	s_addc_u32 s17, s69, 0
	s_lshl_b64 s[0:1], s[52:53], 18
	v_cndmask_b32_e32 v2, v2, v6, vcc
	v_cmp_class_f32_e32 vcc, v0, v149
	s_add_u32 s18, s86, s0
	s_addc_u32 s19, s87, s1
	v_cndmask_b32_e32 v0, v2, v0, vcc
	s_max_i32 s0, s51, 0x1ff
	v_fmamk_f32 v0, v0, 0x3f804189, v156
	s_max_i32 s20, s50, 0x200
	s_add_i32 s21, s0, 0xfffffe01
	v_add_f32_e32 v0, v3, v0
	s_addk_i32 s20, 0xfe00
	s_andn2_b32 s21, s21, 31
	s_lshl_b64 s[0:1], s[66:67], 22
	v_sub_f32_e32 v28, 0x41400000, v0
	s_add_u32 s0, s86, s0
	s_addc_u32 s1, s87, s1
	v_mov_b32_e32 v29, v28
	v_mov_b32_e32 v30, v28
	v_mov_b32_e32 v31, v28
	s_branch .LBB0_337

; DI float red4_sum(float v, int lane) { v += lane_get(v, lane ^ 16); v += lane_get(v, lane ^ 32); return v; }
; DI void attn_phase(const Params& p, const int layer, const int wid_s) {
;     ...
;         if (br == 1) {
; #pragma unroll
;           for (int hp = 0; hp < 2; ++hp) {
;             const float lt = red4_sum(l[hp], lane);
;             const float sc = lt > 0.f ? gate[hp][1] / lt : 0.f;
; #pragma unroll
;             for (int dt = 0; dt < 4; ++dt)
; #pragma unroll
;               for (int j = 0; j < 4; ++j) fin[(hp * 16 + dt * 4 + j) * 64] += O[hp][dt][j] * sc;
;           }
.LBB0_370:
	ds_read2st64_b32 v[198:199], v188 offset0:152 offset1:153
	ds_read2st64_b32 v[200:201], v188 offset0:154 offset1:155
	ds_read2st64_b32 v[202:203], v188 offset0:156 offset1:157
	ds_read2st64_b32 v[204:205], v188 offset0:158 offset1:159
	ds_read2st64_b32 v[206:207], v188 offset0:160 offset1:161
	ds_read2st64_b32 v[208:209], v188 offset0:162 offset1:163
	ds_read2st64_b32 v[210:211], v188 offset0:164 offset1:165
	ds_read2st64_b32 v[212:213], v188 offset0:166 offset1:167
	ds_read2st64_b32 v[214:215], v188 offset0:168 offset1:169
	ds_read2st64_b32 v[216:217], v188 offset0:170 offset1:171
	ds_read2st64_b32 v[218:219], v188 offset0:172 offset1:173
	ds_read2st64_b32 v[220:221], v188 offset0:174 offset1:175
	ds_read2st64_b32 v[222:223], v188 offset0:176 offset1:177
	ds_read2st64_b32 v[224:225], v188 offset0:178 offset1:179
	ds_read2st64_b32 v[226:227], v188 offset0:180 offset1:181
	ds_read2st64_b32 v[228:229], v188 offset0:182 offset1:183
	v_mov_b32_e32 v6, v2
	v_mov_b32_e32 v7, v3
	s_waitcnt lgkmcnt(0)
	s_nop 1
	v_permlane16_swap_b32_e32 v6, v2
	v_permlane16_swap_b32_e32 v7, v3
	v_pk_add_f32 v[6:7], v[2:3], v[6:7]
	v_mov_b32_e32 v60, v6
	v_mov_b32_e32 v61, v7
	s_waitcnt lgkmcnt(0)
	s_nop 1
	v_permlane32_swap_b32_e32 v60, v6
	v_permlane32_swap_b32_e32 v61, v7
	v_pk_add_f32 v[6:7], v[6:7], v[60:61]
	s_nop 0
	v_div_scale_f32 v0, s[6:7], v6, v6, v189
	v_rcp_f32_e32 v80, v0
	s_nop 0
	v_fma_f32 v81, -v0, v80, 1.0
	v_fmac_f32_e32 v80, v81, v80
	v_div_scale_f32 v81, vcc, v189, v6, v189
	v_mul_f32_e32 v82, v81, v80
	v_fma_f32 v83, -v0, v82, v81
	v_fmac_f32_e32 v82, v83, v80
	v_fma_f32 v0, -v0, v82, v81
	v_div_fmas_f32 v0, v0, v80, v82
	v_div_fixup_f32 v0, v0, v6, v189
	v_cmp_lt_f32_e32 vcc, 0, v6
	s_nop 1
	v_cndmask_b32_e32 v0, 0, v0, vcc
	v_fma_f32 v6, v64, v0, v198
	v_fmac_f32_e32 v199, v65, v0
	ds_write2st64_b32 v188, v6, v199 offset0:152 offset1:153
	v_fma_f32 v6, v66, v0, v200
	v_fmac_f32_e32 v201, v67, v0
	ds_write2st64_b32 v188, v6, v201 offset0:154 offset1:155
	v_fma_f32 v6, v56, v0, v202
	v_fmac_f32_e32 v203, v57, v0
	ds_write2st64_b32 v188, v6, v203 offset0:156 offset1:157
	v_fma_f32 v6, v58, v0, v204
	v_fmac_f32_e32 v205, v59, v0
	ds_write2st64_b32 v188, v6, v205 offset0:158 offset1:159
	v_fma_f32 v6, v52, v0, v206
	v_fmac_f32_e32 v207, v53, v0
	ds_write2st64_b32 v188, v6, v207 offset0:160 offset1:161
	v_fma_f32 v6, v54, v0, v208
	v_fmac_f32_e32 v209, v55, v0
	ds_write2st64_b32 v188, v6, v209 offset0:162 offset1:163
	v_fma_f32 v6, v48, v0, v210
	v_fmac_f32_e32 v211, v49, v0
	ds_write2st64_b32 v188, v6, v211 offset0:164 offset1:165
	v_div_scale_f32 v6, s[6:7], v7, v7, v191
	v_rcp_f32_e32 v60, v6
	v_fma_f32 v61, v50, v0, v212
	v_fmac_f32_e32 v213, v51, v0
	ds_write2st64_b32 v188, v61, v213 offset0:166 offset1:167
	v_fma_f32 v0, -v6, v60, 1.0
	v_fmac_f32_e32 v60, v0, v60
	v_div_scale_f32 v0, vcc, v191, v7, v191
	v_mul_f32_e32 v61, v0, v60
	v_fma_f32 v62, -v6, v61, v0
	v_fmac_f32_e32 v61, v62, v60
	v_fma_f32 v0, -v6, v61, v0
	v_div_fmas_f32 v0, v0, v60, v61
	v_div_fixup_f32 v0, v0, v7, v191
	v_cmp_lt_f32_e32 vcc, 0, v7
	s_nop 1
	v_cndmask_b32_e32 v0, 0, v0, vcc
	v_fma_f32 v6, v46, v0, v216
	v_fmac_f32_e32 v217, v47, v0
	ds_write2st64_b32 v188, v6, v217 offset0:170 offset1:171
	v_fma_f32 v6, v40, v0, v218
	v_fmac_f32_e32 v219, v41, v0
	v_fma_f32 v60, v44, v0, v214
	v_fmac_f32_e32 v215, v45, v0
	ds_write2st64_b32 v188, v6, v219 offset0:172 offset1:173
	ds_write2st64_b32 v188, v60, v215 offset0:168 offset1:169
	v_fma_f32 v60, v42, v0, v220
	v_fmac_f32_e32 v221, v43, v0
	ds_write2st64_b32 v188, v60, v221 offset0:174 offset1:175
	v_fma_f32 v6, v36, v0, v222
	v_fmac_f32_e32 v223, v37, v0
	ds_write2st64_b32 v188, v6, v223 offset0:176 offset1:177
	v_fma_f32 v6, v38, v0, v224
	v_fmac_f32_e32 v225, v39, v0
	ds_write2st64_b32 v188, v6, v225 offset0:178 offset1:179
	v_fma_f32 v6, v32, v0, v226
	v_fmac_f32_e32 v227, v33, v0
	ds_write2st64_b32 v188, v6, v227 offset0:180 offset1:181
	v_fma_f32 v6, v34, v0, v228
	v_fmac_f32_e32 v229, v35, v0
	ds_write2st64_b32 v188, v6, v229 offset0:182 offset1:183
	s_cbranch_execnz .LBB0_336
; DI float red4_sum(float v, int lane) { v += lane_get(v, lane ^ 16); v += lane_get(v, lane ^ 32); return v; }
; DI void attn_phase(const Params& p, const int layer, const int wid_s) {
;     ...
;         } else {
;           int t_late = t; asm volatile("" : "+v"(t_late));
; #pragma unroll
;           for (int hp = 0; hp < 2; ++hp) {
;             const float lt = red4_sum(l[hp], lane);
;             const float sc = lt > 0.f ? gate[hp][2] / lt : 0.f;
; #pragma unroll
;             for (int dt = 0; dt < 4; ++dt) {
;               half4 o;
; #pragma unroll
;               for (int j = 0; j < 4; ++j) o[j] = (h16)(fin[(hp * 16 + dt * 4 + j) * 64] + O[hp][dt][j] * sc);
;               *(half4*)(mix + ((size_t)b * SEQ + t_late) * 1024 + 256 + (hh0 + hp) * 64 + dt * 16 + fq * 4) = o;
;             }
;           }
.LBB0_371:
	ds_read2st64_b32 v[198:199], v188 offset0:152 offset1:153
	ds_read2st64_b32 v[200:201], v188 offset0:154 offset1:155
	ds_read2st64_b32 v[202:203], v188 offset0:156 offset1:157
	ds_read2st64_b32 v[204:205], v188 offset0:158 offset1:159
	ds_read2st64_b32 v[206:207], v188 offset0:160 offset1:161
	ds_read2st64_b32 v[208:209], v188 offset0:162 offset1:163
	ds_read2st64_b32 v[210:211], v188 offset0:164 offset1:165
	ds_read2st64_b32 v[212:213], v188 offset0:166 offset1:167
	ds_read2st64_b32 v[214:215], v188 offset0:168 offset1:169
	ds_read2st64_b32 v[216:217], v188 offset0:170 offset1:171
	ds_read2st64_b32 v[218:219], v188 offset0:172 offset1:173
	ds_read2st64_b32 v[220:221], v188 offset0:174 offset1:175
	ds_read2st64_b32 v[222:223], v188 offset0:176 offset1:177
	ds_read2st64_b32 v[224:225], v188 offset0:178 offset1:179
	ds_read2st64_b32 v[226:227], v188 offset0:180 offset1:181
	ds_read2st64_b32 v[228:229], v188 offset0:182 offset1:183
	v_mov_b32_e32 v6, v2
	v_mov_b32_e32 v7, v3
	v_mov_b32_e32 v60, v187
	v_mov_b32_e32 v151, v1
	v_ashrrev_i32_e32 v61, 31, v60
	s_waitcnt lgkmcnt(0)
	s_nop 1
	v_permlane16_swap_b32_e32 v6, v2
	v_permlane16_swap_b32_e32 v7, v3
	v_pk_add_f32 v[2:3], v[2:3], v[6:7]
	v_mov_b32_e32 v6, v2
	v_mov_b32_e32 v7, v3
	v_lshlrev_b64 v[60:61], 11, v[60:61]
	v_lshl_add_u64 v[60:61], s[0:1], 0, v[60:61]
	v_lshl_add_u64 v[60:61], v[60:61], 0, v[150:151]
	s_mov_b64 s[6:7], 0xd20e200
	s_waitcnt lgkmcnt(0)
	s_nop 1
	v_permlane32_swap_b32_e32 v6, v2
	v_permlane32_swap_b32_e32 v7, v3
	v_pk_add_f32 v[2:3], v[2:3], v[6:7]
	v_lshl_add_u64 v[60:61], v[60:61], 0, s[6:7]
	v_div_scale_f32 v0, s[6:7], v2, v2, v190
	v_rcp_f32_e32 v70, v0
	v_lshl_add_u64 v[6:7], s[26:27], 1, v[60:61]
	v_fma_f32 v71, -v0, v70, 1.0
	v_fmac_f32_e32 v70, v71, v70
	v_div_scale_f32 v71, vcc, v190, v2, v190
	v_mul_f32_e32 v72, v71, v70
	v_fma_f32 v73, -v0, v72, v71
	v_fmac_f32_e32 v72, v73, v70
	v_fma_f32 v0, -v0, v72, v71
	v_div_fmas_f32 v0, v0, v70, v72
	v_div_fixup_f32 v0, v0, v2, v190
	v_cmp_lt_f32_e32 vcc, 0, v2
	v_div_scale_f32 v2, s[6:7], v3, v3, v192
	s_nop 0
	v_cndmask_b32_e32 v0, 0, v0, vcc
	v_pk_fma_f32 v[62:63], v[64:65], v[0:1], v[198:199] op_sel_hi:[1,0,1]
	v_pk_fma_f32 v[64:65], v[66:67], v[0:1], v[200:201] op_sel_hi:[1,0,1]
	v_cvt_pk_f16_f32 v62, v62, v63
	v_cvt_pk_f16_f32 v63, v64, v65
	flat_store_dwordx2 v[6:7], v[62:63]
	s_nop 1
	v_pk_fma_f32 v[56:57], v[56:57], v[0:1], v[202:203] op_sel_hi:[1,0,1]
	v_pk_fma_f32 v[58:59], v[58:59], v[0:1], v[204:205] op_sel_hi:[1,0,1]
	v_cvt_pk_f16_f32 v56, v56, v57
	v_cvt_pk_f16_f32 v57, v58, v59
	flat_store_dwordx2 v[6:7], v[56:57] offset:32
	s_nop 1
	v_pk_fma_f32 v[52:53], v[52:53], v[0:1], v[206:207] op_sel_hi:[1,0,1]
	v_pk_fma_f32 v[54:55], v[54:55], v[0:1], v[208:209] op_sel_hi:[1,0,1]
	v_cvt_pk_f16_f32 v52, v52, v53
	v_cvt_pk_f16_f32 v53, v54, v55
	flat_store_dwordx2 v[6:7], v[52:53] offset:64
	s_nop 1
	v_pk_fma_f32 v[48:49], v[48:49], v[0:1], v[210:211] op_sel_hi:[1,0,1]
	v_rcp_f32_e32 v52, v2
	v_pk_fma_f32 v[50:51], v[50:51], v[0:1], v[212:213] op_sel_hi:[1,0,1]
	v_cvt_pk_f16_f32 v48, v48, v49
	v_cvt_pk_f16_f32 v49, v50, v51
	v_fma_f32 v0, -v2, v52, 1.0
	v_fmac_f32_e32 v52, v0, v52
	v_div_scale_f32 v0, vcc, v192, v3, v192
	flat_store_dwordx2 v[6:7], v[48:49] offset:96
	s_nop 1
	v_mul_f32_e32 v6, v0, v52
	v_fma_f32 v7, -v2, v6, v0
	v_fmac_f32_e32 v6, v7, v52
	v_fma_f32 v0, -v2, v6, v0
	v_div_fmas_f32 v0, v0, v52, v6
	v_div_fixup_f32 v0, v0, v3, v192
	v_cmp_lt_f32_e32 vcc, 0, v3
	v_lshl_add_u64 v[2:3], s[48:49], 1, v[60:61]
	s_nop 0
	v_cndmask_b32_e32 v0, 0, v0, vcc
	v_pk_fma_f32 v[6:7], v[44:45], v[0:1], v[214:215] op_sel_hi:[1,0,1]
	v_pk_fma_f32 v[44:45], v[46:47], v[0:1], v[216:217] op_sel_hi:[1,0,1]
	v_cvt_pk_f16_f32 v6, v6, v7
	v_cvt_pk_f16_f32 v7, v44, v45
	flat_store_dwordx2 v[2:3], v[6:7]
	s_nop 1
	v_pk_fma_f32 v[6:7], v[40:41], v[0:1], v[218:219] op_sel_hi:[1,0,1]
	v_pk_fma_f32 v[40:41], v[42:43], v[0:1], v[220:221] op_sel_hi:[1,0,1]
	v_cvt_pk_f16_f32 v6, v6, v7
	v_cvt_pk_f16_f32 v7, v40, v41
	flat_store_dwordx2 v[2:3], v[6:7] offset:32
	s_nop 1
	v_pk_fma_f32 v[6:7], v[36:37], v[0:1], v[222:223] op_sel_hi:[1,0,1]
	v_pk_fma_f32 v[36:37], v[38:39], v[0:1], v[224:225] op_sel_hi:[1,0,1]
	v_cvt_pk_f16_f32 v6, v6, v7
	v_cvt_pk_f16_f32 v7, v36, v37
	flat_store_dwordx2 v[2:3], v[6:7] offset:64
	s_nop 1
	v_pk_fma_f32 v[6:7], v[32:33], v[0:1], v[226:227] op_sel_hi:[1,0,1]
	v_pk_fma_f32 v[32:33], v[34:35], v[0:1], v[228:229] op_sel_hi:[1,0,1]
	v_cvt_pk_f16_f32 v6, v6, v7
	v_cvt_pk_f16_f32 v7, v32, v33
	flat_store_dwordx2 v[2:3], v[6:7] offset:96
	s_nop 1
	s_branch .LBB0_336
